# v11 hand-written combine + band-tile skipping in the diagonal steps (fully masked wave-tiles skip QK/softmax/PV)
# speedup vs baseline: 1.1557x; 1.0060x over previous
; #define GASP __attribute__((address_space(1)))
;   #define DMA_K(t,slot) glds16(ksrc+(long)(t)*KVBLK*DM,(unsigned)__builtin_amdgcn_readfirstlane(kdst+(slot)))
;   #define DMA_V(t,slot) glds16(vsrc+(long)(t)*KVBLK*DM,(unsigned)__builtin_amdgcn_readfirstlane(vdst+(slot)))
; template<int THRL> __device__ __forceinline__ void attn_unit(int b,int qc,int vc,int qb,const bf16*Q,const bf16*__restrict__ K,const bf16*__restrict__ V,bf16*O,char*shm,const int tid){
;   const int lane=tid&63,r32=lane&31,hi=lane>>5; const int wid=__builtin_amdgcn_readfirstlane(tid>>6);
;   const long rowbase=(long)b*SEQ; const int q0=qb*QB;
;   const bf16*Qw=Q+(rowbase+q0+wid*QBLK)*DM+qc;
;   const bf16*Kh=K+rowbase*DM+qc,*Vh=V+rowbase*DM+vc;
;   const unsigned lds0=(unsigned)(uintptr_t)shm;
;   float*wsf=(float*)(shm+LDS_WS)+wid*64;
;   const bf16*ksrc=Kh+(long)lane*DM+wid*8;
;   const bf16*vsrc=Vh+(long)(16*(wid&3)+(lane>>2))*DM+(wid>>2)*32+(lane&3)*8;
;   const unsigned kdst=lds0+LDS_K+wid*1024, vdst=lds0+LDS_V+wid*1024;
;     ...
;   const int vb0=(int)(lds0+LDS_V)+((lane>>4)&1)*32+(lane&3)*8+(4*hi+((lane&15)>>2))*64;
;   const char*Kbase=shm+LDS_K; bf16x8 kf[8];
;   const lds_cptr shm3=(lds_cptr)shm; const lds_cptr kp0=shm3+LDS_K+hi*1024+r32*16; const lds_cptr vp0=shm3+LDS_V+((lane>>4)&1)*32+(lane&3)*8+(4*hi+((lane&15)>>2))*64;
;   const int NT=(q0+QB)/KVBLK;
;   DMA_K(0,0);DMA_V(0,0);DMA_K(1,SLOTB);
;   bf16x8 qr[4];
;   #pragma unroll
;   for(int d0=0;d0<4;++d0)qr[d0]=*(const GASP bf16x8*)(&Qw[(long)r32*DM+d0*16+hi*8]);
;   float zf_=0.f;asm volatile("":"+v"(zf_));float mhat=zf_,l_reg=zf_;f32x16 o[2],negm;
;   #pragma unroll
;   for(int r=0;r<16;++r){o[0][r]=zf_;o[1][r]=zf_;negm[r]=zf_;}
;   asm volatile("":"+v"(negm));
.Lat_qi_loop:
.Lat_unit:
	s_cmp_eq_u32 s73, 0
	s_cselect_b32 s36, s59, s57
	s_cmp_eq_u32 s73, 1
	s_cselect_b32 s36, s58, s36
	s_cmp_eq_u32 s73, 2
	s_cselect_b32 s36, s60, s36
	s_lshl_b32 s54, s46, 5
	s_lshr_b32 s55, s46, 6
	s_mov_b32 s6, s75
	s_mov_b32 s7, 0
	s_lshl_b64 s[6:7], s[6:7], 23
	s_add_u32 s6, s6, s8
	s_addc_u32 s7, s7, s9
	s_lshl_b32 s32, s61, 1
	s_lshl_b32 s21, s72, 7
	s_add_i32 s21, s21, s32
	s_add_u32 s0, s6, 0x29a00000
	s_addc_u32 s1, s7, 0
	s_add_u32 s0, s0, s21
	s_addc_u32 s1, s1, 0
	s_add_u32 s4, s6, 0x2da00000
	s_addc_u32 s5, s7, 0
	s_add_u32 s4, s4, s32
	s_addc_u32 s5, s5, 0
	s_lshl_b32 s37, s36, 19
	s_add_u32 s30, s6, 0x25a00000
	s_addc_u32 s31, s7, 0
	s_add_u32 s30, s30, s37
	s_addc_u32 s31, s31, 0
	s_add_u32 s30, s30, s21
	s_addc_u32 s31, s31, 0
	s_add_u32 s6, s6, 0xda00000
	s_addc_u32 s7, s7, 0
	s_add_u32 s6, s6, s37
	s_addc_u32 s7, s7, 0
	s_add_u32 s6, s6, s32
	s_addc_u32 s7, s7, 0
	s_lshl_b32 s21, s72, 26
	s_add_u32 s6, s6, s21
	s_addc_u32 s7, s7, 0
	s_lshr_b32 s21, s46, 1
	v_lshlrev_b32_e32 v222, 11, v239
	v_add_u32_e32 v222, s21, v222
	s_lshr_b32 s21, s46, 5
	s_and_b32 s32, s21, 3
	s_lshl_b32 s32, s32, 15
	s_lshr_b32 s37, s21, 2
	s_lshl_b32 s37, s37, 6
	s_or_b32 s32, s32, s37
	v_lshrrev_b32_e32 v243, 2, v239
	v_lshlrev_b32_e32 v243, 11, v243
	v_and_b32_e32 v244, 3, v239
	v_lshl_or_b32 v223, v244, 4, v243
	v_or_b32_e32 v223, s32, v223
	v_add_u32_e32 v224, 0x80, v223
	v_lshrrev_b32_e32 v243, 5, v239
	v_and_b32_e32 v244, 31, v239
	v_add_u32_e32 v253, s46, v244
	v_lshlrev_b32_e32 v252, 11, v253
	v_lshl_or_b32 v252, v243, 4, v252
	v_lshlrev_b32_e32 v225, 2, v243
	v_sub_u32_e32 v225, v253, v225
	v_lshlrev_b32_e32 v219, 4, v244
	v_lshl_or_b32 v219, v243, 10, v219
	s_lshl_b32 s21, s46, 3
	s_add_i32 s21, s21, 0x12000
	v_lshl_add_u32 v226, v244, 2, s21
	v_lshl_add_u32 v227, v243, 4, s21
	s_lshl_b32 s21, s46, 7
	s_add_i32 s21, s21, 0x12800
	v_lshl_add_u32 v228, v244, 1, s21
	v_lshl_add_u32 v228, v243, 9, v228
	v_lshrrev_b32_e32 v253, 3, v239
	v_and_b32_e32 v244, 7, v239
	v_lshlrev_b32_e32 v244, 4, v244
	v_lshl_add_u32 v229, v253, 7, s21
	v_add_u32_e32 v229, v229, v244
	v_add_u32_e32 v253, s46, v253
	v_lshl_or_b32 v251, v253, 11, v244
	v_bfe_u32 v244, v239, 4, 1
	v_lshlrev_b32_e32 v244, 5, v244
	v_and_b32_e32 v253, 3, v239
	v_lshl_or_b32 v244, v253, 3, v244
	v_bfe_u32 v253, v239, 2, 2
	v_lshl_add_u32 v253, v243, 2, v253
	v_lshl_or_b32 v204, v253, 6, v244
	v_mov_b32_e32 v241, 0xff800000
	v_mov_b32_e32 v210, 0
	v_mov_b32_e32 v211, 0
	s_mov_b32 m0, s54
	s_nop 0
	global_load_lds_dwordx4 v222, s[0:1]
	s_add_u32 s0, s0, 0x20000
	s_addc_u32 s1, s1, 0
	s_add_i32 m0, s54, 0x6000
	s_nop 0
	global_load_lds_dwordx4 v223, s[4:5]
	s_add_i32 m0, s54, 0xc000
	s_nop 0
	global_load_lds_dwordx4 v224, s[4:5]
	s_add_u32 s4, s4, 0x20000
	s_addc_u32 s5, s5, 0
	s_add_i32 m0, s54, 0x2000
	s_nop 0
	global_load_lds_dwordx4 v222, s[0:1]
	s_add_u32 s0, s0, 0x20000
	s_addc_u32 s1, s1, 0
	global_load_dwordx4 v[144:147], v252, s[30:31] offset:0
	global_load_dwordx4 v[148:151], v252, s[30:31] offset:32
	global_load_dwordx4 v[152:155], v252, s[30:31] offset:64
	global_load_dwordx4 v[156:159], v252, s[30:31] offset:96
	s_add_i32 m0, s54, 0x4000
	s_nop 0
	global_load_lds_dwordx4 v222, s[0:1]
	s_add_u32 s0, s0, 0x20000
	s_addc_u32 s1, s1, 0
	v_mov_b64_e32 v[0:1], 0
	v_mov_b64_e32 v[2:3], 0
	v_mov_b64_e32 v[4:5], 0
	v_mov_b64_e32 v[6:7], 0
	v_mov_b64_e32 v[8:9], 0
	v_mov_b64_e32 v[10:11], 0
	v_mov_b64_e32 v[12:13], 0
	v_mov_b64_e32 v[14:15], 0
	v_mov_b64_e32 v[16:17], 0
	v_mov_b64_e32 v[18:19], 0
	v_mov_b64_e32 v[20:21], 0
	v_mov_b64_e32 v[22:23], 0
	v_mov_b64_e32 v[24:25], 0
	v_mov_b64_e32 v[26:27], 0
	v_mov_b64_e32 v[28:29], 0
	v_mov_b64_e32 v[30:31], 0
	v_mov_b64_e32 v[32:33], 0
	v_mov_b64_e32 v[34:35], 0
	v_mov_b64_e32 v[36:37], 0
	v_mov_b64_e32 v[38:39], 0
	v_mov_b64_e32 v[40:41], 0
	v_mov_b64_e32 v[42:43], 0
	v_mov_b64_e32 v[44:45], 0
	v_mov_b64_e32 v[46:47], 0
	v_mov_b64_e32 v[48:49], 0
	v_mov_b64_e32 v[50:51], 0
	v_mov_b64_e32 v[52:53], 0
	v_mov_b64_e32 v[54:55], 0
	v_mov_b64_e32 v[56:57], 0
	v_mov_b64_e32 v[58:59], 0
	v_mov_b64_e32 v[60:61], 0
	v_mov_b64_e32 v[62:63], 0
	s_waitcnt vmcnt(1) lgkmcnt(0)
	s_barrier
; __device__ __forceinline__ void cmask(f32x16&p0,f32x16&p1,int jb,int qrel,int hi){
;   const float NEG=-INFINITY; int kb=64*jb+4*hi;
;   #pragma unroll
;   for(int r=0;r<16;++r){int kv=kb+(r&3)+8*(r>>2); if(kv>qrel)p0[r]=NEG; if(kv+32>qrel)p1[r]=NEG;}
; }
; __device__ __forceinline__ void qkt(f32x16&p0,f32x16&p1,const char*Kslot,const bf16x8*qr,const f32x16&negm,int r32,int hi){
;   const char*kb=Kslot+hi*1024+r32*16;
;   #pragma unroll
;   for(int d0=0;d0<4;++d0){
;     const bf16x8 b0=*reinterpret_cast<const bf16x8*>(kb+d0*2048);
;     const bf16x8 b1=*reinterpret_cast<const bf16x8*>(kb+d0*2048+512);
;     if(d0==0){p0=__builtin_amdgcn_mfma_f32_32x32x16_bf16(b0,qr[0],negm,0,0,0);p1=__builtin_amdgcn_mfma_f32_32x32x16_bf16(b1,qr[0],negm,0,0,0);}
;     else{p0=__builtin_amdgcn_mfma_f32_32x32x16_bf16(b0,qr[d0],p0,0,0,0);p1=__builtin_amdgcn_mfma_f32_32x32x16_bf16(b1,qr[d0],p1,0,0,0);}}
; }
	ds_read_b128 v[176:179], v219 offset:0
	ds_read_b128 v[180:183], v219 offset:512
	ds_read_b128 v[184:187], v219 offset:2048
	ds_read_b128 v[188:191], v219 offset:2560
	ds_read_b128 v[192:195], v219 offset:4096
	ds_read_b128 v[196:199], v219 offset:4608
	ds_read_b128 v[200:203], v219 offset:6144
	ds_read_b128 v[206:209], v219 offset:6656
	s_waitcnt lgkmcnt(7)
	v_mfma_f32_32x32x16_bf16 v[80:95], v[176:179], v[144:147], 0
	s_waitcnt lgkmcnt(6)
	v_mfma_f32_32x32x16_bf16 v[96:111], v[180:183], v[144:147], 0
	s_waitcnt lgkmcnt(5)
	v_mfma_f32_32x32x16_bf16 v[80:95], v[184:187], v[148:151], v[80:95]
	s_waitcnt lgkmcnt(4)
	v_mfma_f32_32x32x16_bf16 v[96:111], v[188:191], v[148:151], v[96:111]
	s_waitcnt lgkmcnt(3)
	v_mfma_f32_32x32x16_bf16 v[80:95], v[192:195], v[152:155], v[80:95]
	s_waitcnt lgkmcnt(2)
	v_mfma_f32_32x32x16_bf16 v[96:111], v[196:199], v[152:155], v[96:111]
	s_waitcnt lgkmcnt(1)
	v_mfma_f32_32x32x16_bf16 v[80:95], v[200:203], v[156:159], v[80:95]
	s_waitcnt lgkmcnt(0)
	v_mfma_f32_32x32x16_bf16 v[96:111], v[206:209], v[156:159], v[96:111]
	s_nop 11
	s_cmp_lg_u32 s36, 0
	s_cbranch_scc1 .Lat_s0nomask_1
	v_cmp_gt_i32_e64 s[28:29], 0, v225
	v_cmp_gt_i32_e64 s[30:31], 32, v225
	v_cmp_gt_i32_e64 s[34:35], 1, v225
	v_cndmask_b32_e64 v80, v80, v241, s[28:29]
	v_cmp_gt_i32_e64 s[28:29], 33, v225
	v_cndmask_b32_e64 v96, v96, v241, s[30:31]
	v_cmp_gt_i32_e64 s[30:31], 2, v225
	v_cndmask_b32_e64 v81, v81, v241, s[34:35]
	v_cmp_gt_i32_e64 s[34:35], 34, v225
	v_cndmask_b32_e64 v97, v97, v241, s[28:29]
	v_cmp_gt_i32_e64 s[28:29], 3, v225
	v_cndmask_b32_e64 v82, v82, v241, s[30:31]
	v_cmp_gt_i32_e64 s[30:31], 35, v225
	v_cndmask_b32_e64 v98, v98, v241, s[34:35]
	v_cmp_gt_i32_e64 s[34:35], 8, v225
	v_cndmask_b32_e64 v83, v83, v241, s[28:29]
	v_cmp_gt_i32_e64 s[28:29], 40, v225
	v_cndmask_b32_e64 v99, v99, v241, s[30:31]
	v_cmp_gt_i32_e64 s[30:31], 9, v225
	v_cndmask_b32_e64 v84, v84, v241, s[34:35]
	v_cmp_gt_i32_e64 s[34:35], 41, v225
	v_cndmask_b32_e64 v100, v100, v241, s[28:29]
	v_cmp_gt_i32_e64 s[28:29], 10, v225
	v_cndmask_b32_e64 v85, v85, v241, s[30:31]
	v_cmp_gt_i32_e64 s[30:31], 42, v225
	v_cndmask_b32_e64 v101, v101, v241, s[34:35]
	v_cmp_gt_i32_e64 s[34:35], 11, v225
	v_cndmask_b32_e64 v86, v86, v241, s[28:29]
	v_cmp_gt_i32_e64 s[28:29], 43, v225
	v_cndmask_b32_e64 v102, v102, v241, s[30:31]
	v_cmp_gt_i32_e64 s[30:31], 16, v225
	v_cndmask_b32_e64 v87, v87, v241, s[34:35]
	v_cmp_gt_i32_e64 s[34:35], 48, v225
	v_cndmask_b32_e64 v103, v103, v241, s[28:29]
	v_cmp_gt_i32_e64 s[28:29], 17, v225
	v_cndmask_b32_e64 v88, v88, v241, s[30:31]
	v_cmp_gt_i32_e64 s[30:31], 49, v225
	v_cndmask_b32_e64 v104, v104, v241, s[34:35]
	v_cmp_gt_i32_e64 s[34:35], 18, v225
	v_cndmask_b32_e64 v89, v89, v241, s[28:29]
	v_cmp_gt_i32_e64 s[28:29], 50, v225
	v_cndmask_b32_e64 v105, v105, v241, s[30:31]
	v_cmp_gt_i32_e64 s[30:31], 19, v225
	v_cndmask_b32_e64 v90, v90, v241, s[34:35]
	v_cmp_gt_i32_e64 s[34:35], 51, v225
	v_cndmask_b32_e64 v106, v106, v241, s[28:29]
	v_cmp_gt_i32_e64 s[28:29], 24, v225
	v_cndmask_b32_e64 v91, v91, v241, s[30:31]
	v_cmp_gt_i32_e64 s[30:31], 56, v225
	v_cndmask_b32_e64 v107, v107, v241, s[34:35]
	v_cmp_gt_i32_e64 s[34:35], 25, v225
	v_cndmask_b32_e64 v92, v92, v241, s[28:29]
	v_cmp_gt_i32_e64 s[28:29], 57, v225
	v_cndmask_b32_e64 v108, v108, v241, s[30:31]
	v_cmp_gt_i32_e64 s[30:31], 26, v225
	v_cndmask_b32_e64 v93, v93, v241, s[34:35]
	v_cmp_gt_i32_e64 s[34:35], 58, v225
	v_cndmask_b32_e64 v109, v109, v241, s[28:29]
	v_cmp_gt_i32_e64 s[28:29], 27, v225
	v_cndmask_b32_e64 v94, v94, v241, s[30:31]
	v_cmp_gt_i32_e64 s[30:31], 59, v225
	v_cndmask_b32_e64 v110, v110, v241, s[34:35]
	v_cndmask_b32_e64 v95, v95, v241, s[28:29]
	v_cndmask_b32_e64 v111, v111, v241, s[30:31]

.Lat_step_T3:
	s_cmp_lt_u32 s55, 1
	s_cbranch_scc1 .Lat_T3_light
	v_add_u32_e32 v243, s16, v204
	ds_read_b64_tr_b16 v[214:215], v243 offset:24576
	ds_read_b64_tr_b16 v[216:217], v243 offset:25088
	v_mfma_f32_32x32x16_bf16 v[112:127], v[176:179], v[144:147], v[64:79]
	v_add_f32_e32 v245, v80, v81
	v_add_f32_e32 v245, v82, v245
	v_add_f32_e32 v245, v83, v245
	v_add_f32_e32 v245, v84, v245
	v_add_f32_e32 v245, v85, v245
	v_cvt_pk_bf16_f32 v160, v80, v81
	v_cvt_pk_bf16_f32 v161, v82, v83
	ds_read_b64_tr_b16 v[80:81], v243 offset:28672
	ds_read_b64_tr_b16 v[82:83], v243 offset:29184
	v_mfma_f32_32x32x16_bf16 v[128:143], v[180:183], v[144:147], v[64:79]
	v_add_f32_e32 v245, v86, v245
	v_add_f32_e32 v245, v87, v245
	v_add_f32_e32 v245, v88, v245
	v_add_f32_e32 v245, v89, v245
	v_cvt_pk_bf16_f32 v162, v84, v85
	v_cvt_pk_bf16_f32 v163, v86, v87
	ds_read_b64_tr_b16 v[84:85], v243 offset:25600
	ds_read_b64_tr_b16 v[86:87], v243 offset:26112
	v_mfma_f32_32x32x16_bf16 v[112:127], v[184:187], v[148:151], v[112:127]
	v_add_f32_e32 v245, v90, v245
	v_add_f32_e32 v245, v91, v245
	v_add_f32_e32 v245, v92, v245
	v_add_f32_e32 v245, v93, v245
	v_cvt_pk_bf16_f32 v164, v88, v89
	v_cvt_pk_bf16_f32 v165, v90, v91
	ds_read_b64_tr_b16 v[88:89], v243 offset:29696
	ds_read_b64_tr_b16 v[90:91], v243 offset:30208
	v_mfma_f32_32x32x16_bf16 v[128:143], v[188:191], v[148:151], v[128:143]
	v_add_f32_e32 v245, v94, v245
	v_add_f32_e32 v245, v95, v245
	v_add_f32_e32 v245, v96, v245
	v_add_f32_e32 v245, v97, v245
	v_cvt_pk_bf16_f32 v166, v92, v93
	v_cvt_pk_bf16_f32 v167, v94, v95
	ds_read_b64_tr_b16 v[92:93], v243 offset:26624
	ds_read_b64_tr_b16 v[94:95], v243 offset:27136
	v_mfma_f32_32x32x16_bf16 v[112:127], v[192:195], v[152:155], v[112:127]
	v_add_f32_e32 v245, v98, v245
	v_add_f32_e32 v245, v99, v245
	v_add_f32_e32 v245, v100, v245
	v_add_f32_e32 v245, v101, v245
	v_cvt_pk_bf16_f32 v168, v96, v97
	v_cvt_pk_bf16_f32 v169, v98, v99
	ds_read_b64_tr_b16 v[96:97], v243 offset:30720
	ds_read_b64_tr_b16 v[98:99], v243 offset:31232
	v_mfma_f32_32x32x16_bf16 v[128:143], v[196:199], v[152:155], v[128:143]
	v_add_f32_e32 v245, v102, v245
	v_add_f32_e32 v245, v103, v245
	v_add_f32_e32 v245, v104, v245
	v_add_f32_e32 v245, v105, v245
	v_cvt_pk_bf16_f32 v170, v100, v101
	v_cvt_pk_bf16_f32 v171, v102, v103
	ds_read_b64_tr_b16 v[100:101], v243 offset:27648
	ds_read_b64_tr_b16 v[102:103], v243 offset:28160
	v_mfma_f32_32x32x16_bf16 v[112:127], v[200:203], v[156:159], v[112:127]
	v_add_f32_e32 v245, v106, v245
	v_add_f32_e32 v245, v107, v245
	v_add_f32_e32 v245, v108, v245
	v_add_f32_e32 v245, v109, v245
	v_cvt_pk_bf16_f32 v172, v104, v105
	v_cvt_pk_bf16_f32 v173, v106, v107
	ds_read_b64_tr_b16 v[104:105], v243 offset:31744
	ds_read_b64_tr_b16 v[106:107], v243 offset:32256
	v_mfma_f32_32x32x16_bf16 v[128:143], v[206:209], v[156:159], v[128:143]
	v_add_f32_e32 v245, v110, v245
	v_add_f32_e32 v245, v111, v245
	v_cvt_pk_bf16_f32 v174, v108, v109
	v_cvt_pk_bf16_f32 v175, v110, v111
	v_add_f32_e32 v211, v211, v245
	v_add_u32_e32 v244, s18, v219
	s_waitcnt lgkmcnt(8)
	v_mfma_f32_32x32x16_bf16 v[0:15], v[160:163], v[214:217], v[0:15]
	v_add_u32_e32 v242, 0xffffffc0, v225
	v_cmp_gt_i32_e64 s[28:29], 0, v242
	v_cmp_gt_i32_e64 s[30:31], 1, v242
	v_cmp_gt_i32_e64 s[34:35], 2, v242
	v_cndmask_b32_e64 v112, v112, v241, s[28:29]
	v_cmp_gt_i32_e64 s[28:29], 3, v242
	v_cndmask_b32_e64 v113, v113, v241, s[30:31]
	v_cmp_gt_i32_e64 s[30:31], 8, v242
	v_cndmask_b32_e64 v114, v114, v241, s[34:35]
	v_cmp_gt_i32_e64 s[34:35], 9, v242
	ds_read_b64_tr_b16 v[214:215], v243 offset:49152
	ds_read_b64_tr_b16 v[216:217], v243 offset:49664
	v_mfma_f32_32x32x16_bf16 v[16:31], v[160:163], v[80:83], v[16:31]
	v_cndmask_b32_e64 v115, v115, v241, s[28:29]
	v_cmp_gt_i32_e64 s[28:29], 10, v242
	v_cndmask_b32_e64 v116, v116, v241, s[30:31]
	v_cmp_gt_i32_e64 s[30:31], 11, v242
	v_cndmask_b32_e64 v117, v117, v241, s[34:35]
	v_cmp_gt_i32_e64 s[34:35], 16, v242
	v_cndmask_b32_e64 v118, v118, v241, s[28:29]
	v_cmp_gt_i32_e64 s[28:29], 17, v242
	v_cndmask_b32_e64 v119, v119, v241, s[30:31]
	v_cmp_gt_i32_e64 s[30:31], 18, v242
	ds_read_b64_tr_b16 v[80:81], v243 offset:53248
	ds_read_b64_tr_b16 v[82:83], v243 offset:53760
	v_mfma_f32_32x32x16_bf16 v[0:15], v[164:167], v[84:87], v[0:15]
	s_add_i32 s21, s18, s54
	s_add_i32 m0, s21, 0x6000
	v_cndmask_b32_e64 v120, v120, v241, s[34:35]
	v_cmp_gt_i32_e64 s[34:35], 19, v242
	v_cndmask_b32_e64 v121, v121, v241, s[28:29]
	v_cmp_gt_i32_e64 s[28:29], 24, v242
	v_cndmask_b32_e64 v122, v122, v241, s[30:31]
	v_cmp_gt_i32_e64 s[30:31], 25, v242
	v_cndmask_b32_e64 v123, v123, v241, s[34:35]
	v_cmp_gt_i32_e64 s[34:35], 26, v242
	v_cndmask_b32_e64 v124, v124, v241, s[28:29]
	v_cmp_gt_i32_e64 s[28:29], 27, v242
	ds_read_b64_tr_b16 v[84:85], v243 offset:50176
	ds_read_b64_tr_b16 v[86:87], v243 offset:50688
	global_load_lds_dwordx4 v223, s[4:5]
	v_mfma_f32_32x32x16_bf16 v[16:31], v[164:167], v[88:91], v[16:31]
	s_add_i32 m0, s21, 0xc000
	v_cndmask_b32_e64 v125, v125, v241, s[30:31]
	v_cmp_gt_i32_e64 s[30:31], 32, v242
	v_cndmask_b32_e64 v126, v126, v241, s[34:35]
	v_cmp_gt_i32_e64 s[34:35], 33, v242
	v_cndmask_b32_e64 v127, v127, v241, s[28:29]
	v_cmp_gt_i32_e64 s[28:29], 34, v242
	v_cndmask_b32_e64 v128, v128, v241, s[30:31]
	v_cmp_gt_i32_e64 s[30:31], 35, v242
	v_cndmask_b32_e64 v129, v129, v241, s[34:35]
	v_cmp_gt_i32_e64 s[34:35], 40, v242
	ds_read_b64_tr_b16 v[88:89], v243 offset:54272
	ds_read_b64_tr_b16 v[90:91], v243 offset:54784
	global_load_lds_dwordx4 v224, s[4:5]
	s_add_u32 s4, s4, 0x20000
	s_addc_u32 s5, s5, 0
	s_waitcnt lgkmcnt(8)
	v_mfma_f32_32x32x16_bf16 v[0:15], v[168:171], v[92:95], v[0:15]
	v_cndmask_b32_e64 v130, v130, v241, s[28:29]
	v_cmp_gt_i32_e64 s[28:29], 41, v242
	v_cndmask_b32_e64 v131, v131, v241, s[30:31]
	v_cmp_gt_i32_e64 s[30:31], 42, v242
	v_cndmask_b32_e64 v132, v132, v241, s[34:35]
	v_cmp_gt_i32_e64 s[34:35], 43, v242
	v_cndmask_b32_e64 v133, v133, v241, s[28:29]
	v_cmp_gt_i32_e64 s[28:29], 48, v242
	v_cndmask_b32_e64 v134, v134, v241, s[30:31]
	v_cmp_gt_i32_e64 s[30:31], 49, v242
	ds_read_b64_tr_b16 v[92:93], v243 offset:51200
	ds_read_b64_tr_b16 v[94:95], v243 offset:51712
	v_mfma_f32_32x32x16_bf16 v[16:31], v[168:171], v[96:99], v[16:31]
	v_cndmask_b32_e64 v135, v135, v241, s[34:35]
	v_cmp_gt_i32_e64 s[34:35], 50, v242
	v_cndmask_b32_e64 v136, v136, v241, s[28:29]
	v_cmp_gt_i32_e64 s[28:29], 51, v242
	v_cndmask_b32_e64 v137, v137, v241, s[30:31]
	v_cmp_gt_i32_e64 s[30:31], 56, v242
	v_cndmask_b32_e64 v138, v138, v241, s[34:35]
	v_cmp_gt_i32_e64 s[34:35], 57, v242
	v_cndmask_b32_e64 v139, v139, v241, s[28:29]
	v_cmp_gt_i32_e64 s[28:29], 58, v242
	ds_read_b64_tr_b16 v[96:97], v243 offset:55296
	ds_read_b64_tr_b16 v[98:99], v243 offset:55808
	v_mfma_f32_32x32x16_bf16 v[0:15], v[172:175], v[100:103], v[0:15]
	v_cndmask_b32_e64 v140, v140, v241, s[30:31]
	v_cmp_gt_i32_e64 s[30:31], 59, v242
	v_cndmask_b32_e64 v141, v141, v241, s[34:35]
	v_cndmask_b32_e64 v142, v142, v241, s[28:29]
	v_cndmask_b32_e64 v143, v143, v241, s[30:31]
	v_max3_f32 v246, v112, v113, v114
	v_max3_f32 v247, v115, v116, v117
	v_max3_f32 v246, v246, v118, v119
	v_max3_f32 v247, v247, v120, v121
	v_max3_f32 v246, v246, v122, v123
	ds_read_b64_tr_b16 v[100:101], v243 offset:52224
	ds_read_b64_tr_b16 v[102:103], v243 offset:52736
	v_mfma_f32_32x32x16_bf16 v[16:31], v[172:175], v[104:107], v[16:31]
	v_max3_f32 v247, v247, v124, v125
	v_max3_f32 v246, v246, v126, v127
	v_max3_f32 v247, v247, v128, v129
	v_max3_f32 v246, v246, v130, v131
	v_max3_f32 v247, v247, v132, v133
	v_max3_f32 v246, v246, v134, v135
	v_max3_f32 v247, v247, v136, v137
	v_max3_f32 v246, v246, v138, v139
	v_max3_f32 v247, v247, v140, v141
	v_max3_f32 v246, v246, v142, v143
	ds_read_b64_tr_b16 v[104:105], v243 offset:56320
	ds_read_b64_tr_b16 v[106:107], v243 offset:56832
	s_waitcnt lgkmcnt(8)
	v_mfma_f32_32x32x16_bf16 v[32:47], v[160:163], v[214:217], v[32:47]
	v_max_f32_e32 v248, v246, v247
	v_mov_b32_e32 v246, v248
	s_nop 1
	v_permlane32_swap_b32_e32 v248, v246
	v_max_f32_e32 v248, v248, v246
	ds_read_b128 v[176:179], v244 offset:0
	ds_read_b128 v[180:183], v244 offset:512
	v_cmp_lt_f32_e32 vcc, s87, v248
	s_cbranch_vccnz .Lat_rare_T3

.Lat_noresc_T3:
	s_mov_b32 s21, s16
	s_mov_b32 s16, s17
	s_mov_b32 s17, s18
	s_mov_b32 s18, s21
	s_branch .Lat_T3_end
.Lat_T3_light:
	s_cmp_lt_u32 s55, 0
	s_cbranch_scc1 .Lat_T3_empty
	v_add_u32_e32 v243, s16, v204
	ds_read_b64_tr_b16 v[214:215], v243 offset:24576
	ds_read_b64_tr_b16 v[216:217], v243 offset:25088
	v_add_f32_e32 v245, v80, v81
	v_add_f32_e32 v245, v82, v245
	v_add_f32_e32 v245, v83, v245
	v_add_f32_e32 v245, v84, v245
	v_add_f32_e32 v245, v85, v245
	v_cvt_pk_bf16_f32 v160, v80, v81
	v_cvt_pk_bf16_f32 v161, v82, v83
	ds_read_b64_tr_b16 v[80:81], v243 offset:28672
	ds_read_b64_tr_b16 v[82:83], v243 offset:29184
	v_add_f32_e32 v245, v86, v245
	v_add_f32_e32 v245, v87, v245
	v_add_f32_e32 v245, v88, v245
	v_add_f32_e32 v245, v89, v245
	v_cvt_pk_bf16_f32 v162, v84, v85
	v_cvt_pk_bf16_f32 v163, v86, v87
	ds_read_b64_tr_b16 v[84:85], v243 offset:25600
	ds_read_b64_tr_b16 v[86:87], v243 offset:26112
	v_add_f32_e32 v245, v90, v245
	v_add_f32_e32 v245, v91, v245
	v_add_f32_e32 v245, v92, v245
	v_add_f32_e32 v245, v93, v245
	v_cvt_pk_bf16_f32 v164, v88, v89
	v_cvt_pk_bf16_f32 v165, v90, v91
	ds_read_b64_tr_b16 v[88:89], v243 offset:29696
	ds_read_b64_tr_b16 v[90:91], v243 offset:30208
	v_add_f32_e32 v245, v94, v245
	v_add_f32_e32 v245, v95, v245
	v_add_f32_e32 v245, v96, v245
	v_add_f32_e32 v245, v97, v245
	v_cvt_pk_bf16_f32 v166, v92, v93
	v_cvt_pk_bf16_f32 v167, v94, v95
	ds_read_b64_tr_b16 v[92:93], v243 offset:26624
	ds_read_b64_tr_b16 v[94:95], v243 offset:27136
	v_add_f32_e32 v245, v98, v245
	v_add_f32_e32 v245, v99, v245
	v_add_f32_e32 v245, v100, v245
	v_add_f32_e32 v245, v101, v245
	v_cvt_pk_bf16_f32 v168, v96, v97
	v_cvt_pk_bf16_f32 v169, v98, v99
	ds_read_b64_tr_b16 v[96:97], v243 offset:30720
	ds_read_b64_tr_b16 v[98:99], v243 offset:31232
	v_add_f32_e32 v245, v102, v245
	v_add_f32_e32 v245, v103, v245
	v_add_f32_e32 v245, v104, v245
	v_add_f32_e32 v245, v105, v245
	v_cvt_pk_bf16_f32 v170, v100, v101
	v_cvt_pk_bf16_f32 v171, v102, v103
	ds_read_b64_tr_b16 v[100:101], v243 offset:27648
	ds_read_b64_tr_b16 v[102:103], v243 offset:28160
	v_add_f32_e32 v245, v106, v245
	v_add_f32_e32 v245, v107, v245
	v_add_f32_e32 v245, v108, v245
	v_add_f32_e32 v245, v109, v245
	v_cvt_pk_bf16_f32 v172, v104, v105
	v_cvt_pk_bf16_f32 v173, v106, v107
	ds_read_b64_tr_b16 v[104:105], v243 offset:31744
	ds_read_b64_tr_b16 v[106:107], v243 offset:32256
	v_add_f32_e32 v245, v110, v245
	v_add_f32_e32 v245, v111, v245
	v_cvt_pk_bf16_f32 v174, v108, v109
	v_cvt_pk_bf16_f32 v175, v110, v111
	v_add_f32_e32 v211, v211, v245
	s_waitcnt lgkmcnt(8)
	v_mfma_f32_32x32x16_bf16 v[0:15], v[160:163], v[214:217], v[0:15]
	ds_read_b64_tr_b16 v[214:215], v243 offset:49152
	ds_read_b64_tr_b16 v[216:217], v243 offset:49664
	v_mfma_f32_32x32x16_bf16 v[16:31], v[160:163], v[80:83], v[16:31]
	ds_read_b64_tr_b16 v[80:81], v243 offset:53248
	ds_read_b64_tr_b16 v[82:83], v243 offset:53760
	v_mfma_f32_32x32x16_bf16 v[0:15], v[164:167], v[84:87], v[0:15]
	s_add_i32 s21, s18, s54
	s_add_i32 m0, s21, 0x6000
	ds_read_b64_tr_b16 v[84:85], v243 offset:50176
	ds_read_b64_tr_b16 v[86:87], v243 offset:50688
	global_load_lds_dwordx4 v223, s[4:5]
	v_mfma_f32_32x32x16_bf16 v[16:31], v[164:167], v[88:91], v[16:31]
	s_add_i32 m0, s21, 0xc000
	ds_read_b64_tr_b16 v[88:89], v243 offset:54272
	ds_read_b64_tr_b16 v[90:91], v243 offset:54784
	global_load_lds_dwordx4 v224, s[4:5]
	s_add_u32 s4, s4, 0x20000
	s_addc_u32 s5, s5, 0
	s_waitcnt lgkmcnt(8)
	v_mfma_f32_32x32x16_bf16 v[0:15], v[168:171], v[92:95], v[0:15]
	ds_read_b64_tr_b16 v[92:93], v243 offset:51200
	ds_read_b64_tr_b16 v[94:95], v243 offset:51712
	v_mfma_f32_32x32x16_bf16 v[16:31], v[168:171], v[96:99], v[16:31]
	ds_read_b64_tr_b16 v[96:97], v243 offset:55296
	ds_read_b64_tr_b16 v[98:99], v243 offset:55808
	v_mfma_f32_32x32x16_bf16 v[0:15], v[172:175], v[100:103], v[0:15]
	ds_read_b64_tr_b16 v[100:101], v243 offset:52224
	ds_read_b64_tr_b16 v[102:103], v243 offset:52736
	v_mfma_f32_32x32x16_bf16 v[16:31], v[172:175], v[104:107], v[16:31]
	ds_read_b64_tr_b16 v[104:105], v243 offset:56320
	ds_read_b64_tr_b16 v[106:107], v243 offset:56832
	s_waitcnt lgkmcnt(8)
	v_mfma_f32_32x32x16_bf16 v[32:47], v[160:163], v[214:217], v[32:47]
	v_mfma_f32_32x32x16_bf16 v[48:63], v[160:163], v[80:83], v[48:63]
	v_mfma_f32_32x32x16_bf16 v[32:47], v[164:167], v[84:87], v[32:47]
	v_mfma_f32_32x32x16_bf16 v[48:63], v[164:167], v[88:91], v[48:63]
	s_waitcnt lgkmcnt(0)
	v_mfma_f32_32x32x16_bf16 v[32:47], v[168:171], v[92:95], v[32:47]
	v_mfma_f32_32x32x16_bf16 v[48:63], v[168:171], v[96:99], v[48:63]
	v_mfma_f32_32x32x16_bf16 v[32:47], v[172:175], v[100:103], v[32:47]
	v_mfma_f32_32x32x16_bf16 v[48:63], v[172:175], v[104:107], v[48:63]
	s_waitcnt vmcnt(2) lgkmcnt(0)
	s_barrier
	s_mov_b32 s21, s16
	s_mov_b32 s16, s17
	s_mov_b32 s17, s18
	s_mov_b32 s18, s21
	s_branch .Lat_T3_end
.Lat_T3_empty:
	s_add_i32 s21, s18, s54
	s_add_i32 m0, s21, 0x6000
	s_nop 0
	global_load_lds_dwordx4 v223, s[4:5]
	s_add_i32 m0, s21, 0xc000
	s_nop 0
	global_load_lds_dwordx4 v224, s[4:5]
	s_add_u32 s4, s4, 0x20000
	s_addc_u32 s5, s5, 0
	s_waitcnt vmcnt(2) lgkmcnt(0)
	s_barrier
	s_mov_b32 s21, s16
	s_mov_b32 s16, s17
	s_mov_b32 s17, s18
	s_mov_b32 s18, s21
.Lat_T3_end:
.Lat_step_T2:
	s_cmp_lt_u32 s55, 2
	s_cbranch_scc1 .Lat_T2_light
	v_add_u32_e32 v243, s16, v204
	ds_read_b64_tr_b16 v[214:215], v243 offset:24576
	ds_read_b64_tr_b16 v[216:217], v243 offset:25088
	v_mfma_f32_32x32x16_bf16 v[80:95], v[176:179], v[144:147], v[64:79]
	v_add_f32_e32 v245, v112, v113
	v_add_f32_e32 v245, v114, v245
	v_add_f32_e32 v245, v115, v245
	v_add_f32_e32 v245, v116, v245
	v_add_f32_e32 v245, v117, v245
	v_cvt_pk_bf16_f32 v160, v112, v113
	v_cvt_pk_bf16_f32 v161, v114, v115
	ds_read_b64_tr_b16 v[112:113], v243 offset:28672
	ds_read_b64_tr_b16 v[114:115], v243 offset:29184
	v_mfma_f32_32x32x16_bf16 v[96:111], v[180:183], v[144:147], v[64:79]
	v_add_f32_e32 v245, v118, v245
	v_add_f32_e32 v245, v119, v245
	v_add_f32_e32 v245, v120, v245
	v_add_f32_e32 v245, v121, v245
	v_cvt_pk_bf16_f32 v162, v116, v117
	v_cvt_pk_bf16_f32 v163, v118, v119
	ds_read_b64_tr_b16 v[116:117], v243 offset:25600
	ds_read_b64_tr_b16 v[118:119], v243 offset:26112
	v_mfma_f32_32x32x16_bf16 v[80:95], v[184:187], v[148:151], v[80:95]
	v_add_f32_e32 v245, v122, v245
	v_add_f32_e32 v245, v123, v245
	v_add_f32_e32 v245, v124, v245
	v_add_f32_e32 v245, v125, v245
	v_cvt_pk_bf16_f32 v164, v120, v121
	v_cvt_pk_bf16_f32 v165, v122, v123
	ds_read_b64_tr_b16 v[120:121], v243 offset:29696
	ds_read_b64_tr_b16 v[122:123], v243 offset:30208
	v_mfma_f32_32x32x16_bf16 v[96:111], v[188:191], v[148:151], v[96:111]
	v_add_f32_e32 v245, v126, v245
	v_add_f32_e32 v245, v127, v245
	v_add_f32_e32 v245, v128, v245
	v_add_f32_e32 v245, v129, v245
	v_cvt_pk_bf16_f32 v166, v124, v125
	v_cvt_pk_bf16_f32 v167, v126, v127
	ds_read_b64_tr_b16 v[124:125], v243 offset:26624
	ds_read_b64_tr_b16 v[126:127], v243 offset:27136
	v_mfma_f32_32x32x16_bf16 v[80:95], v[192:195], v[152:155], v[80:95]
	v_add_f32_e32 v245, v130, v245
	v_add_f32_e32 v245, v131, v245
	v_add_f32_e32 v245, v132, v245
	v_add_f32_e32 v245, v133, v245
	v_cvt_pk_bf16_f32 v168, v128, v129
	v_cvt_pk_bf16_f32 v169, v130, v131
	ds_read_b64_tr_b16 v[128:129], v243 offset:30720
	ds_read_b64_tr_b16 v[130:131], v243 offset:31232
	v_mfma_f32_32x32x16_bf16 v[96:111], v[196:199], v[152:155], v[96:111]
	v_add_f32_e32 v245, v134, v245
	v_add_f32_e32 v245, v135, v245
	v_add_f32_e32 v245, v136, v245
	v_add_f32_e32 v245, v137, v245
	v_cvt_pk_bf16_f32 v170, v132, v133
	v_cvt_pk_bf16_f32 v171, v134, v135
	ds_read_b64_tr_b16 v[132:133], v243 offset:27648
	ds_read_b64_tr_b16 v[134:135], v243 offset:28160
	v_mfma_f32_32x32x16_bf16 v[80:95], v[200:203], v[156:159], v[80:95]
	v_add_f32_e32 v245, v138, v245
	v_add_f32_e32 v245, v139, v245
	v_add_f32_e32 v245, v140, v245
	v_add_f32_e32 v245, v141, v245
	v_cvt_pk_bf16_f32 v172, v136, v137
	v_cvt_pk_bf16_f32 v173, v138, v139
	ds_read_b64_tr_b16 v[136:137], v243 offset:31744
	ds_read_b64_tr_b16 v[138:139], v243 offset:32256
	v_mfma_f32_32x32x16_bf16 v[96:111], v[206:209], v[156:159], v[96:111]
	v_add_f32_e32 v245, v142, v245
	v_add_f32_e32 v245, v143, v245
	v_cvt_pk_bf16_f32 v174, v140, v141
	v_cvt_pk_bf16_f32 v175, v142, v143
	v_add_f32_e32 v211, v211, v245
	v_add_u32_e32 v244, s18, v219
	s_waitcnt lgkmcnt(8)
	v_mfma_f32_32x32x16_bf16 v[0:15], v[160:163], v[214:217], v[0:15]
	v_add_u32_e32 v242, 0xffffff80, v225
	v_cmp_gt_i32_e64 s[28:29], 0, v242
	v_cmp_gt_i32_e64 s[30:31], 1, v242
	v_cmp_gt_i32_e64 s[34:35], 2, v242
	v_cndmask_b32_e64 v80, v80, v241, s[28:29]
	v_cmp_gt_i32_e64 s[28:29], 3, v242
	v_cndmask_b32_e64 v81, v81, v241, s[30:31]
	v_cmp_gt_i32_e64 s[30:31], 8, v242
	v_cndmask_b32_e64 v82, v82, v241, s[34:35]
	v_cmp_gt_i32_e64 s[34:35], 9, v242
	ds_read_b64_tr_b16 v[214:215], v243 offset:49152
	ds_read_b64_tr_b16 v[216:217], v243 offset:49664
	v_mfma_f32_32x32x16_bf16 v[16:31], v[160:163], v[112:115], v[16:31]
	v_cndmask_b32_e64 v83, v83, v241, s[28:29]
	v_cmp_gt_i32_e64 s[28:29], 10, v242
	v_cndmask_b32_e64 v84, v84, v241, s[30:31]
	v_cmp_gt_i32_e64 s[30:31], 11, v242
	v_cndmask_b32_e64 v85, v85, v241, s[34:35]
	v_cmp_gt_i32_e64 s[34:35], 16, v242
	v_cndmask_b32_e64 v86, v86, v241, s[28:29]
	v_cmp_gt_i32_e64 s[28:29], 17, v242
	v_cndmask_b32_e64 v87, v87, v241, s[30:31]
	v_cmp_gt_i32_e64 s[30:31], 18, v242
	ds_read_b64_tr_b16 v[112:113], v243 offset:53248
	ds_read_b64_tr_b16 v[114:115], v243 offset:53760
	v_mfma_f32_32x32x16_bf16 v[0:15], v[164:167], v[116:119], v[0:15]
	s_add_i32 s21, s18, s54
	s_add_i32 m0, s21, 0x6000
	v_cndmask_b32_e64 v88, v88, v241, s[34:35]
	v_cmp_gt_i32_e64 s[34:35], 19, v242
	v_cndmask_b32_e64 v89, v89, v241, s[28:29]
	v_cmp_gt_i32_e64 s[28:29], 24, v242
	v_cndmask_b32_e64 v90, v90, v241, s[30:31]
	v_cmp_gt_i32_e64 s[30:31], 25, v242
	v_cndmask_b32_e64 v91, v91, v241, s[34:35]
	v_cmp_gt_i32_e64 s[34:35], 26, v242
	v_cndmask_b32_e64 v92, v92, v241, s[28:29]
	v_cmp_gt_i32_e64 s[28:29], 27, v242
	ds_read_b64_tr_b16 v[116:117], v243 offset:50176
	ds_read_b64_tr_b16 v[118:119], v243 offset:50688
	global_load_lds_dwordx4 v223, s[4:5]
	v_mfma_f32_32x32x16_bf16 v[16:31], v[164:167], v[120:123], v[16:31]
	s_add_i32 m0, s21, 0xc000
	v_cndmask_b32_e64 v93, v93, v241, s[30:31]
	v_cmp_gt_i32_e64 s[30:31], 32, v242
	v_cndmask_b32_e64 v94, v94, v241, s[34:35]
	v_cmp_gt_i32_e64 s[34:35], 33, v242
	v_cndmask_b32_e64 v95, v95, v241, s[28:29]
	v_cmp_gt_i32_e64 s[28:29], 34, v242
	v_cndmask_b32_e64 v96, v96, v241, s[30:31]
	v_cmp_gt_i32_e64 s[30:31], 35, v242
	v_cndmask_b32_e64 v97, v97, v241, s[34:35]
	v_cmp_gt_i32_e64 s[34:35], 40, v242
	ds_read_b64_tr_b16 v[120:121], v243 offset:54272
	ds_read_b64_tr_b16 v[122:123], v243 offset:54784
	global_load_lds_dwordx4 v224, s[4:5]
	s_add_u32 s4, s4, 0x20000
	s_addc_u32 s5, s5, 0
	s_waitcnt lgkmcnt(8)
	v_mfma_f32_32x32x16_bf16 v[0:15], v[168:171], v[124:127], v[0:15]
	v_cndmask_b32_e64 v98, v98, v241, s[28:29]
	v_cmp_gt_i32_e64 s[28:29], 41, v242
	v_cndmask_b32_e64 v99, v99, v241, s[30:31]
	v_cmp_gt_i32_e64 s[30:31], 42, v242
	v_cndmask_b32_e64 v100, v100, v241, s[34:35]
	v_cmp_gt_i32_e64 s[34:35], 43, v242
	v_cndmask_b32_e64 v101, v101, v241, s[28:29]
	v_cmp_gt_i32_e64 s[28:29], 48, v242
	v_cndmask_b32_e64 v102, v102, v241, s[30:31]
	v_cmp_gt_i32_e64 s[30:31], 49, v242
	ds_read_b64_tr_b16 v[124:125], v243 offset:51200
	ds_read_b64_tr_b16 v[126:127], v243 offset:51712
	v_mfma_f32_32x32x16_bf16 v[16:31], v[168:171], v[128:131], v[16:31]
	v_cndmask_b32_e64 v103, v103, v241, s[34:35]
	v_cmp_gt_i32_e64 s[34:35], 50, v242
	v_cndmask_b32_e64 v104, v104, v241, s[28:29]
	v_cmp_gt_i32_e64 s[28:29], 51, v242
	v_cndmask_b32_e64 v105, v105, v241, s[30:31]
	v_cmp_gt_i32_e64 s[30:31], 56, v242
	v_cndmask_b32_e64 v106, v106, v241, s[34:35]
	v_cmp_gt_i32_e64 s[34:35], 57, v242
	v_cndmask_b32_e64 v107, v107, v241, s[28:29]
	v_cmp_gt_i32_e64 s[28:29], 58, v242
	ds_read_b64_tr_b16 v[128:129], v243 offset:55296
	ds_read_b64_tr_b16 v[130:131], v243 offset:55808
	v_mfma_f32_32x32x16_bf16 v[0:15], v[172:175], v[132:135], v[0:15]
	v_cndmask_b32_e64 v108, v108, v241, s[30:31]
	v_cmp_gt_i32_e64 s[30:31], 59, v242
	v_cndmask_b32_e64 v109, v109, v241, s[34:35]
	v_cndmask_b32_e64 v110, v110, v241, s[28:29]
	v_cndmask_b32_e64 v111, v111, v241, s[30:31]
	v_max3_f32 v246, v80, v81, v82
	v_max3_f32 v247, v83, v84, v85
	v_max3_f32 v246, v246, v86, v87
	v_max3_f32 v247, v247, v88, v89
	v_max3_f32 v246, v246, v90, v91
	ds_read_b64_tr_b16 v[132:133], v243 offset:52224
	ds_read_b64_tr_b16 v[134:135], v243 offset:52736
	v_mfma_f32_32x32x16_bf16 v[16:31], v[172:175], v[136:139], v[16:31]
	v_max3_f32 v247, v247, v92, v93
	v_max3_f32 v246, v246, v94, v95
	v_max3_f32 v247, v247, v96, v97
	v_max3_f32 v246, v246, v98, v99
	v_max3_f32 v247, v247, v100, v101
	v_max3_f32 v246, v246, v102, v103
	v_max3_f32 v247, v247, v104, v105
	v_max3_f32 v246, v246, v106, v107
	v_max3_f32 v247, v247, v108, v109
	v_max3_f32 v246, v246, v110, v111
	ds_read_b64_tr_b16 v[136:137], v243 offset:56320
	ds_read_b64_tr_b16 v[138:139], v243 offset:56832
	s_waitcnt lgkmcnt(8)
	v_mfma_f32_32x32x16_bf16 v[32:47], v[160:163], v[214:217], v[32:47]
	v_max_f32_e32 v248, v246, v247
	v_mov_b32_e32 v246, v248
	s_nop 1
	v_permlane32_swap_b32_e32 v248, v246
	v_max_f32_e32 v248, v248, v246
	ds_read_b128 v[176:179], v244 offset:0
	ds_read_b128 v[180:183], v244 offset:512
	v_cmp_lt_f32_e32 vcc, s87, v248
	s_cbranch_vccnz .Lat_rare_T2

.Lat_T2_light:
	s_cmp_lt_u32 s55, 1
	s_cbranch_scc1 .Lat_T2_empty
	v_add_u32_e32 v243, s16, v204
	ds_read_b64_tr_b16 v[214:215], v243 offset:24576
	ds_read_b64_tr_b16 v[216:217], v243 offset:25088
	v_add_f32_e32 v245, v112, v113
	v_add_f32_e32 v245, v114, v245
	v_add_f32_e32 v245, v115, v245
	v_add_f32_e32 v245, v116, v245
	v_add_f32_e32 v245, v117, v245
	v_cvt_pk_bf16_f32 v160, v112, v113
	v_cvt_pk_bf16_f32 v161, v114, v115
	ds_read_b64_tr_b16 v[112:113], v243 offset:28672
	ds_read_b64_tr_b16 v[114:115], v243 offset:29184
	v_add_f32_e32 v245, v118, v245
	v_add_f32_e32 v245, v119, v245
	v_add_f32_e32 v245, v120, v245
	v_add_f32_e32 v245, v121, v245
	v_cvt_pk_bf16_f32 v162, v116, v117
	v_cvt_pk_bf16_f32 v163, v118, v119
	ds_read_b64_tr_b16 v[116:117], v243 offset:25600
	ds_read_b64_tr_b16 v[118:119], v243 offset:26112
	v_add_f32_e32 v245, v122, v245
	v_add_f32_e32 v245, v123, v245
	v_add_f32_e32 v245, v124, v245
	v_add_f32_e32 v245, v125, v245
	v_cvt_pk_bf16_f32 v164, v120, v121
	v_cvt_pk_bf16_f32 v165, v122, v123
	ds_read_b64_tr_b16 v[120:121], v243 offset:29696
	ds_read_b64_tr_b16 v[122:123], v243 offset:30208
	v_add_f32_e32 v245, v126, v245
	v_add_f32_e32 v245, v127, v245
	v_add_f32_e32 v245, v128, v245
	v_add_f32_e32 v245, v129, v245
	v_cvt_pk_bf16_f32 v166, v124, v125
	v_cvt_pk_bf16_f32 v167, v126, v127
	ds_read_b64_tr_b16 v[124:125], v243 offset:26624
	ds_read_b64_tr_b16 v[126:127], v243 offset:27136
	v_add_f32_e32 v245, v130, v245
	v_add_f32_e32 v245, v131, v245
	v_add_f32_e32 v245, v132, v245
	v_add_f32_e32 v245, v133, v245
	v_cvt_pk_bf16_f32 v168, v128, v129
	v_cvt_pk_bf16_f32 v169, v130, v131
	ds_read_b64_tr_b16 v[128:129], v243 offset:30720
	ds_read_b64_tr_b16 v[130:131], v243 offset:31232
	v_add_f32_e32 v245, v134, v245
	v_add_f32_e32 v245, v135, v245
	v_add_f32_e32 v245, v136, v245
	v_add_f32_e32 v245, v137, v245
	v_cvt_pk_bf16_f32 v170, v132, v133
	v_cvt_pk_bf16_f32 v171, v134, v135
	ds_read_b64_tr_b16 v[132:133], v243 offset:27648
	ds_read_b64_tr_b16 v[134:135], v243 offset:28160
	v_add_f32_e32 v245, v138, v245
	v_add_f32_e32 v245, v139, v245
	v_add_f32_e32 v245, v140, v245
	v_add_f32_e32 v245, v141, v245
	v_cvt_pk_bf16_f32 v172, v136, v137
	v_cvt_pk_bf16_f32 v173, v138, v139
	ds_read_b64_tr_b16 v[136:137], v243 offset:31744
	ds_read_b64_tr_b16 v[138:139], v243 offset:32256
	v_add_f32_e32 v245, v142, v245
	v_add_f32_e32 v245, v143, v245
	v_cvt_pk_bf16_f32 v174, v140, v141
	v_cvt_pk_bf16_f32 v175, v142, v143
	v_add_f32_e32 v211, v211, v245
	s_waitcnt lgkmcnt(8)
	v_mfma_f32_32x32x16_bf16 v[0:15], v[160:163], v[214:217], v[0:15]
	ds_read_b64_tr_b16 v[214:215], v243 offset:49152
	ds_read_b64_tr_b16 v[216:217], v243 offset:49664
	v_mfma_f32_32x32x16_bf16 v[16:31], v[160:163], v[112:115], v[16:31]
	ds_read_b64_tr_b16 v[112:113], v243 offset:53248
	ds_read_b64_tr_b16 v[114:115], v243 offset:53760
	v_mfma_f32_32x32x16_bf16 v[0:15], v[164:167], v[116:119], v[0:15]
	s_add_i32 s21, s18, s54
	s_add_i32 m0, s21, 0x6000
	ds_read_b64_tr_b16 v[116:117], v243 offset:50176
	ds_read_b64_tr_b16 v[118:119], v243 offset:50688
	global_load_lds_dwordx4 v223, s[4:5]
	v_mfma_f32_32x32x16_bf16 v[16:31], v[164:167], v[120:123], v[16:31]
	s_add_i32 m0, s21, 0xc000
	ds_read_b64_tr_b16 v[120:121], v243 offset:54272
	ds_read_b64_tr_b16 v[122:123], v243 offset:54784
	global_load_lds_dwordx4 v224, s[4:5]
	s_add_u32 s4, s4, 0x20000
	s_addc_u32 s5, s5, 0
	s_waitcnt lgkmcnt(8)
	v_mfma_f32_32x32x16_bf16 v[0:15], v[168:171], v[124:127], v[0:15]
	ds_read_b64_tr_b16 v[124:125], v243 offset:51200
	ds_read_b64_tr_b16 v[126:127], v243 offset:51712
	v_mfma_f32_32x32x16_bf16 v[16:31], v[168:171], v[128:131], v[16:31]
	ds_read_b64_tr_b16 v[128:129], v243 offset:55296
	ds_read_b64_tr_b16 v[130:131], v243 offset:55808
	v_mfma_f32_32x32x16_bf16 v[0:15], v[172:175], v[132:135], v[0:15]
	ds_read_b64_tr_b16 v[132:133], v243 offset:52224
	ds_read_b64_tr_b16 v[134:135], v243 offset:52736
	v_mfma_f32_32x32x16_bf16 v[16:31], v[172:175], v[136:139], v[16:31]
	ds_read_b64_tr_b16 v[136:137], v243 offset:56320
	ds_read_b64_tr_b16 v[138:139], v243 offset:56832
	s_waitcnt lgkmcnt(8)
	v_mfma_f32_32x32x16_bf16 v[32:47], v[160:163], v[214:217], v[32:47]
	v_mfma_f32_32x32x16_bf16 v[48:63], v[160:163], v[112:115], v[48:63]
	v_mfma_f32_32x32x16_bf16 v[32:47], v[164:167], v[116:119], v[32:47]
	v_mfma_f32_32x32x16_bf16 v[48:63], v[164:167], v[120:123], v[48:63]
	s_waitcnt lgkmcnt(0)
	v_mfma_f32_32x32x16_bf16 v[32:47], v[168:171], v[124:127], v[32:47]
	v_mfma_f32_32x32x16_bf16 v[48:63], v[168:171], v[128:131], v[48:63]
	v_mfma_f32_32x32x16_bf16 v[32:47], v[172:175], v[132:135], v[32:47]
	v_mfma_f32_32x32x16_bf16 v[48:63], v[172:175], v[136:139], v[48:63]
	s_waitcnt vmcnt(0) lgkmcnt(0)
	s_barrier
	s_mov_b32 s21, s16
	s_mov_b32 s16, s17
	s_mov_b32 s17, s18
	s_mov_b32 s18, s21
	s_branch .Lat_T2_end
.Lat_T2_empty:
	s_add_i32 s21, s18, s54
	s_add_i32 m0, s21, 0x6000
	s_nop 0
	global_load_lds_dwordx4 v223, s[4:5]
	s_add_i32 m0, s21, 0xc000
	s_nop 0
	global_load_lds_dwordx4 v224, s[4:5]
	s_add_u32 s4, s4, 0x20000
	s_addc_u32 s5, s5, 0
	s_waitcnt vmcnt(0) lgkmcnt(0)
	s_barrier
	s_mov_b32 s21, s16
	s_mov_b32 s16, s17
	s_mov_b32 s17, s18
	s_mov_b32 s18, s21
.Lat_T2_end:
.Lat_step_T1:
	s_cmp_lt_u32 s55, 3
	s_cbranch_scc1 .Lat_T1_light
	v_add_u32_e32 v243, s16, v204
	ds_read_b64_tr_b16 v[214:215], v243 offset:24576
	ds_read_b64_tr_b16 v[216:217], v243 offset:25088
	v_mfma_f32_32x32x16_bf16 v[112:127], v[176:179], v[144:147], v[64:79]
	v_add_f32_e32 v245, v80, v81
	v_add_f32_e32 v245, v82, v245
	v_add_f32_e32 v245, v83, v245
	v_add_f32_e32 v245, v84, v245
	v_add_f32_e32 v245, v85, v245
	v_cvt_pk_bf16_f32 v160, v80, v81
	v_cvt_pk_bf16_f32 v161, v82, v83
	ds_read_b64_tr_b16 v[80:81], v243 offset:28672
	ds_read_b64_tr_b16 v[82:83], v243 offset:29184
	v_mfma_f32_32x32x16_bf16 v[128:143], v[180:183], v[144:147], v[64:79]
	v_add_f32_e32 v245, v86, v245
	v_add_f32_e32 v245, v87, v245
	v_add_f32_e32 v245, v88, v245
	v_add_f32_e32 v245, v89, v245
	v_cvt_pk_bf16_f32 v162, v84, v85
	v_cvt_pk_bf16_f32 v163, v86, v87
	ds_read_b64_tr_b16 v[84:85], v243 offset:25600
	ds_read_b64_tr_b16 v[86:87], v243 offset:26112
	v_mfma_f32_32x32x16_bf16 v[112:127], v[184:187], v[148:151], v[112:127]
	v_add_f32_e32 v245, v90, v245
	v_add_f32_e32 v245, v91, v245
	v_add_f32_e32 v245, v92, v245
	v_add_f32_e32 v245, v93, v245
	v_cvt_pk_bf16_f32 v164, v88, v89
	v_cvt_pk_bf16_f32 v165, v90, v91
	ds_read_b64_tr_b16 v[88:89], v243 offset:29696
	ds_read_b64_tr_b16 v[90:91], v243 offset:30208
	v_mfma_f32_32x32x16_bf16 v[128:143], v[188:191], v[148:151], v[128:143]
	v_add_f32_e32 v245, v94, v245
	v_add_f32_e32 v245, v95, v245
	v_add_f32_e32 v245, v96, v245
	v_add_f32_e32 v245, v97, v245
	v_cvt_pk_bf16_f32 v166, v92, v93
	v_cvt_pk_bf16_f32 v167, v94, v95
	ds_read_b64_tr_b16 v[92:93], v243 offset:26624
	ds_read_b64_tr_b16 v[94:95], v243 offset:27136
	v_mfma_f32_32x32x16_bf16 v[112:127], v[192:195], v[152:155], v[112:127]
	v_add_f32_e32 v245, v98, v245
	v_add_f32_e32 v245, v99, v245
	v_add_f32_e32 v245, v100, v245
	v_add_f32_e32 v245, v101, v245
	v_cvt_pk_bf16_f32 v168, v96, v97
	v_cvt_pk_bf16_f32 v169, v98, v99
	ds_read_b64_tr_b16 v[96:97], v243 offset:30720
	ds_read_b64_tr_b16 v[98:99], v243 offset:31232
	v_mfma_f32_32x32x16_bf16 v[128:143], v[196:199], v[152:155], v[128:143]
	v_add_f32_e32 v245, v102, v245
	v_add_f32_e32 v245, v103, v245
	v_add_f32_e32 v245, v104, v245
	v_add_f32_e32 v245, v105, v245
	v_cvt_pk_bf16_f32 v170, v100, v101
	v_cvt_pk_bf16_f32 v171, v102, v103
	ds_read_b64_tr_b16 v[100:101], v243 offset:27648
	ds_read_b64_tr_b16 v[102:103], v243 offset:28160
	v_mfma_f32_32x32x16_bf16 v[112:127], v[200:203], v[156:159], v[112:127]
	v_add_f32_e32 v245, v106, v245
	v_add_f32_e32 v245, v107, v245
	v_add_f32_e32 v245, v108, v245
	v_add_f32_e32 v245, v109, v245
	v_cvt_pk_bf16_f32 v172, v104, v105
	v_cvt_pk_bf16_f32 v173, v106, v107
	ds_read_b64_tr_b16 v[104:105], v243 offset:31744
	ds_read_b64_tr_b16 v[106:107], v243 offset:32256
	v_mfma_f32_32x32x16_bf16 v[128:143], v[206:209], v[156:159], v[128:143]
	v_add_f32_e32 v245, v110, v245
	v_add_f32_e32 v245, v111, v245
	v_cvt_pk_bf16_f32 v174, v108, v109
	v_cvt_pk_bf16_f32 v175, v110, v111
	v_add_f32_e32 v211, v211, v245
	s_waitcnt lgkmcnt(8)
	v_mfma_f32_32x32x16_bf16 v[0:15], v[160:163], v[214:217], v[0:15]
	v_add_u32_e32 v242, 0xffffff40, v225
	v_cmp_gt_i32_e64 s[28:29], 0, v242
	v_cmp_gt_i32_e64 s[30:31], 1, v242
	v_cmp_gt_i32_e64 s[34:35], 2, v242
	v_cndmask_b32_e64 v112, v112, v241, s[28:29]
	v_cmp_gt_i32_e64 s[28:29], 3, v242
	v_cndmask_b32_e64 v113, v113, v241, s[30:31]
	v_cmp_gt_i32_e64 s[30:31], 8, v242
	v_cndmask_b32_e64 v114, v114, v241, s[34:35]
	v_cmp_gt_i32_e64 s[34:35], 9, v242
	ds_read_b64_tr_b16 v[214:215], v243 offset:49152
	ds_read_b64_tr_b16 v[216:217], v243 offset:49664
	v_mfma_f32_32x32x16_bf16 v[16:31], v[160:163], v[80:83], v[16:31]
	v_cndmask_b32_e64 v115, v115, v241, s[28:29]
	v_cmp_gt_i32_e64 s[28:29], 10, v242
	v_cndmask_b32_e64 v116, v116, v241, s[30:31]
	v_cmp_gt_i32_e64 s[30:31], 11, v242
	v_cndmask_b32_e64 v117, v117, v241, s[34:35]
	v_cmp_gt_i32_e64 s[34:35], 16, v242
	v_cndmask_b32_e64 v118, v118, v241, s[28:29]
	v_cmp_gt_i32_e64 s[28:29], 17, v242
	v_cndmask_b32_e64 v119, v119, v241, s[30:31]
	v_cmp_gt_i32_e64 s[30:31], 18, v242
	ds_read_b64_tr_b16 v[80:81], v243 offset:53248
	ds_read_b64_tr_b16 v[82:83], v243 offset:53760
	v_mfma_f32_32x32x16_bf16 v[0:15], v[164:167], v[84:87], v[0:15]
	v_cndmask_b32_e64 v120, v120, v241, s[34:35]
	v_cmp_gt_i32_e64 s[34:35], 19, v242
	v_cndmask_b32_e64 v121, v121, v241, s[28:29]
	v_cmp_gt_i32_e64 s[28:29], 24, v242
	v_cndmask_b32_e64 v122, v122, v241, s[30:31]
	v_cmp_gt_i32_e64 s[30:31], 25, v242
	v_cndmask_b32_e64 v123, v123, v241, s[34:35]
	v_cmp_gt_i32_e64 s[34:35], 26, v242
	v_cndmask_b32_e64 v124, v124, v241, s[28:29]
	v_cmp_gt_i32_e64 s[28:29], 27, v242
	ds_read_b64_tr_b16 v[84:85], v243 offset:50176
	ds_read_b64_tr_b16 v[86:87], v243 offset:50688
	v_mfma_f32_32x32x16_bf16 v[16:31], v[164:167], v[88:91], v[16:31]
	v_cndmask_b32_e64 v125, v125, v241, s[30:31]
	v_cmp_gt_i32_e64 s[30:31], 32, v242
	v_cndmask_b32_e64 v126, v126, v241, s[34:35]
	v_cmp_gt_i32_e64 s[34:35], 33, v242
	v_cndmask_b32_e64 v127, v127, v241, s[28:29]
	v_cmp_gt_i32_e64 s[28:29], 34, v242
	v_cndmask_b32_e64 v128, v128, v241, s[30:31]
	v_cmp_gt_i32_e64 s[30:31], 35, v242
	v_cndmask_b32_e64 v129, v129, v241, s[34:35]
	v_cmp_gt_i32_e64 s[34:35], 40, v242
	ds_read_b64_tr_b16 v[88:89], v243 offset:54272
	ds_read_b64_tr_b16 v[90:91], v243 offset:54784
	s_waitcnt lgkmcnt(8)
	v_mfma_f32_32x32x16_bf16 v[0:15], v[168:171], v[92:95], v[0:15]
	v_cndmask_b32_e64 v130, v130, v241, s[28:29]
	v_cmp_gt_i32_e64 s[28:29], 41, v242
	v_cndmask_b32_e64 v131, v131, v241, s[30:31]
	v_cmp_gt_i32_e64 s[30:31], 42, v242
	v_cndmask_b32_e64 v132, v132, v241, s[34:35]
	v_cmp_gt_i32_e64 s[34:35], 43, v242
	v_cndmask_b32_e64 v133, v133, v241, s[28:29]
	v_cmp_gt_i32_e64 s[28:29], 48, v242
	v_cndmask_b32_e64 v134, v134, v241, s[30:31]
	v_cmp_gt_i32_e64 s[30:31], 49, v242
	ds_read_b64_tr_b16 v[92:93], v243 offset:51200
	ds_read_b64_tr_b16 v[94:95], v243 offset:51712
	v_mfma_f32_32x32x16_bf16 v[16:31], v[168:171], v[96:99], v[16:31]
	v_cndmask_b32_e64 v135, v135, v241, s[34:35]
	v_cmp_gt_i32_e64 s[34:35], 50, v242
	v_cndmask_b32_e64 v136, v136, v241, s[28:29]
	v_cmp_gt_i32_e64 s[28:29], 51, v242
	v_cndmask_b32_e64 v137, v137, v241, s[30:31]
	v_cmp_gt_i32_e64 s[30:31], 56, v242
	v_cndmask_b32_e64 v138, v138, v241, s[34:35]
	v_cmp_gt_i32_e64 s[34:35], 57, v242
	v_cndmask_b32_e64 v139, v139, v241, s[28:29]
	v_cmp_gt_i32_e64 s[28:29], 58, v242
	ds_read_b64_tr_b16 v[96:97], v243 offset:55296
	ds_read_b64_tr_b16 v[98:99], v243 offset:55808
	v_mfma_f32_32x32x16_bf16 v[0:15], v[172:175], v[100:103], v[0:15]
	v_cndmask_b32_e64 v140, v140, v241, s[30:31]
	v_cmp_gt_i32_e64 s[30:31], 59, v242
	v_cndmask_b32_e64 v141, v141, v241, s[34:35]
	v_cndmask_b32_e64 v142, v142, v241, s[28:29]
	v_cndmask_b32_e64 v143, v143, v241, s[30:31]
	v_max3_f32 v246, v112, v113, v114
	v_max3_f32 v247, v115, v116, v117
	v_max3_f32 v246, v246, v118, v119
	v_max3_f32 v247, v247, v120, v121
	v_max3_f32 v246, v246, v122, v123
	ds_read_b64_tr_b16 v[100:101], v243 offset:52224
	ds_read_b64_tr_b16 v[102:103], v243 offset:52736
	v_mfma_f32_32x32x16_bf16 v[16:31], v[172:175], v[104:107], v[16:31]
	v_max3_f32 v247, v247, v124, v125
	v_max3_f32 v246, v246, v126, v127
	v_max3_f32 v247, v247, v128, v129
	v_max3_f32 v246, v246, v130, v131
	v_max3_f32 v247, v247, v132, v133
	v_max3_f32 v246, v246, v134, v135
	v_max3_f32 v247, v247, v136, v137
	v_max3_f32 v246, v246, v138, v139
	v_max3_f32 v247, v247, v140, v141
	v_max3_f32 v246, v246, v142, v143
	ds_read_b64_tr_b16 v[104:105], v243 offset:56320
	ds_read_b64_tr_b16 v[106:107], v243 offset:56832
	s_waitcnt lgkmcnt(8)
	v_mfma_f32_32x32x16_bf16 v[32:47], v[160:163], v[214:217], v[32:47]
	v_max_f32_e32 v248, v246, v247
	v_mov_b32_e32 v246, v248
	s_nop 1
	v_permlane32_swap_b32_e32 v248, v246
	v_max_f32_e32 v248, v248, v246
	v_cmp_lt_f32_e32 vcc, s87, v248
	s_cbranch_vccnz .Lat_rare_T1
.Lat_cont_T1:
	v_mfma_f32_32x32x16_bf16 v[48:63], v[160:163], v[80:83], v[48:63]
	v_exp_f32_e32 v112, v112
	v_exp_f32_e32 v113, v113
	v_exp_f32_e32 v114, v114
	v_exp_f32_e32 v115, v115
	v_exp_f32_e32 v116, v116
	v_mfma_f32_32x32x16_bf16 v[32:47], v[164:167], v[84:87], v[32:47]
	v_exp_f32_e32 v117, v117
	v_exp_f32_e32 v118, v118
	v_exp_f32_e32 v119, v119
	v_exp_f32_e32 v120, v120
	v_exp_f32_e32 v121, v121
	v_mfma_f32_32x32x16_bf16 v[48:63], v[164:167], v[88:91], v[48:63]
	v_exp_f32_e32 v122, v122
	v_exp_f32_e32 v123, v123
	v_exp_f32_e32 v124, v124
	v_exp_f32_e32 v125, v125
	v_exp_f32_e32 v126, v126
	s_waitcnt lgkmcnt(0)
	v_mfma_f32_32x32x16_bf16 v[32:47], v[168:171], v[92:95], v[32:47]
	v_exp_f32_e32 v127, v127
	v_exp_f32_e32 v128, v128
	v_exp_f32_e32 v129, v129
	v_exp_f32_e32 v130, v130
	v_exp_f32_e32 v131, v131
	v_mfma_f32_32x32x16_bf16 v[48:63], v[168:171], v[96:99], v[48:63]
	v_exp_f32_e32 v132, v132
	v_exp_f32_e32 v133, v133
	v_exp_f32_e32 v134, v134
	v_exp_f32_e32 v135, v135
	v_mfma_f32_32x32x16_bf16 v[32:47], v[172:175], v[100:103], v[32:47]
	v_exp_f32_e32 v136, v136
	v_exp_f32_e32 v137, v137
	v_exp_f32_e32 v138, v138
	v_exp_f32_e32 v139, v139
	v_mfma_f32_32x32x16_bf16 v[48:63], v[172:175], v[104:107], v[48:63]
	v_exp_f32_e32 v140, v140
	v_exp_f32_e32 v141, v141
	v_exp_f32_e32 v142, v142
	v_exp_f32_e32 v143, v143
	s_cbranch_vccz .Lat_noresc_T1
	s_waitcnt lgkmcnt(0)
	ds_read_b128 v[214:217], v227 offset:0
	s_waitcnt lgkmcnt(0)
	v_pk_mul_f32 v[0:1], v[0:1], v[214:215]
	v_pk_mul_f32 v[2:3], v[2:3], v[216:217]
	v_pk_mul_f32 v[16:17], v[16:17], v[214:215]
	v_pk_mul_f32 v[18:19], v[18:19], v[216:217]
	v_pk_mul_f32 v[32:33], v[32:33], v[214:215]
	v_pk_mul_f32 v[34:35], v[34:35], v[216:217]
	v_pk_mul_f32 v[48:49], v[48:49], v[214:215]
	v_pk_mul_f32 v[50:51], v[50:51], v[216:217]
	ds_read_b128 v[214:217], v227 offset:32
	s_waitcnt lgkmcnt(0)
	v_pk_mul_f32 v[4:5], v[4:5], v[214:215]
	v_pk_mul_f32 v[6:7], v[6:7], v[216:217]
	v_pk_mul_f32 v[20:21], v[20:21], v[214:215]
	v_pk_mul_f32 v[22:23], v[22:23], v[216:217]
	v_pk_mul_f32 v[36:37], v[36:37], v[214:215]
	v_pk_mul_f32 v[38:39], v[38:39], v[216:217]
	v_pk_mul_f32 v[52:53], v[52:53], v[214:215]
	v_pk_mul_f32 v[54:55], v[54:55], v[216:217]
	ds_read_b128 v[214:217], v227 offset:64
	s_waitcnt lgkmcnt(0)
	v_pk_mul_f32 v[8:9], v[8:9], v[214:215]
	v_pk_mul_f32 v[10:11], v[10:11], v[216:217]
	v_pk_mul_f32 v[24:25], v[24:25], v[214:215]
	v_pk_mul_f32 v[26:27], v[26:27], v[216:217]
	v_pk_mul_f32 v[40:41], v[40:41], v[214:215]
	v_pk_mul_f32 v[42:43], v[42:43], v[216:217]
	v_pk_mul_f32 v[56:57], v[56:57], v[214:215]
	v_pk_mul_f32 v[58:59], v[58:59], v[216:217]
	ds_read_b128 v[214:217], v227 offset:96
	s_waitcnt lgkmcnt(0)
	v_pk_mul_f32 v[12:13], v[12:13], v[214:215]
	v_pk_mul_f32 v[14:15], v[14:15], v[216:217]
	v_pk_mul_f32 v[28:29], v[28:29], v[214:215]
	v_pk_mul_f32 v[30:31], v[30:31], v[216:217]
	v_pk_mul_f32 v[44:45], v[44:45], v[214:215]
	v_pk_mul_f32 v[46:47], v[46:47], v[216:217]
	v_pk_mul_f32 v[60:61], v[60:61], v[214:215]
	v_pk_mul_f32 v[62:63], v[62:63], v[216:217]
; #define SBAR() __builtin_amdgcn_sched_barrier(0)
;   #define RESC() do{ if(resc){ asm volatile("s_waitcnt lgkmcnt(0)":::"memory"); \
;       _Pragma("unroll") for(int d_=0;d_<2;++d_) _Pragma("unroll") for(int r=0;r<16;++r)o[d_][r]*=wsf[crow(r,hi)]; } }while(0)
;   #define PKW(P,B) cvtpk_s(P[B],P[B+1])
; template<int THRL> __device__ __forceinline__ void attn_unit(int b,int qc,int vc,int qb,const bf16*Q,const bf16*__restrict__ K,const bf16*__restrict__ V,bf16*O,char*shm,const int tid){
;     ...
;   STEP(pB0,pB1,pA0,pA1,NT-1,false,false,false); RESC();
;   { float sacc=pB0[0]+pB0[1]; _Pragma("unroll") for(int r=2;r<16;++r)sacc+=pB0[r]; _Pragma("unroll") for(int r=0;r<16;++r)sacc+=pB1[r]; l_reg+=sacc;
;     pw0=(u32x4){PKW(pB0,0),PKW(pB0,2),PKW(pB0,4),PKW(pB0,6)};pw1=(u32x4){PKW(pB0,8),PKW(pB0,10),PKW(pB0,12),PKW(pB0,14)};pw2=(u32x4){PKW(pB1,0),PKW(pB1,2),PKW(pB1,4),PKW(pB1,6)};pw3=(u32x4){PKW(pB1,8),PKW(pB1,10),PKW(pB1,12),PKW(pB1,14)};
;     SBAR(); pv(o,vb0+sl_cur,PAF(0),PAF(1),PAF(2),PAF(3)); }
.Lat_noresc_T1:
	s_branch .Lat_T1_end
.Lat_T1_light:
	s_cmp_lt_u32 s55, 2
	s_cbranch_scc1 .Lat_T1_empty
	v_add_u32_e32 v243, s16, v204
	ds_read_b64_tr_b16 v[214:215], v243 offset:24576
	ds_read_b64_tr_b16 v[216:217], v243 offset:25088
	v_add_f32_e32 v245, v80, v81
	v_add_f32_e32 v245, v82, v245
	v_add_f32_e32 v245, v83, v245
	v_add_f32_e32 v245, v84, v245
	v_add_f32_e32 v245, v85, v245
	v_cvt_pk_bf16_f32 v160, v80, v81
	v_cvt_pk_bf16_f32 v161, v82, v83
	ds_read_b64_tr_b16 v[80:81], v243 offset:28672
	ds_read_b64_tr_b16 v[82:83], v243 offset:29184
	v_add_f32_e32 v245, v86, v245
	v_add_f32_e32 v245, v87, v245
	v_add_f32_e32 v245, v88, v245
	v_add_f32_e32 v245, v89, v245
	v_cvt_pk_bf16_f32 v162, v84, v85
	v_cvt_pk_bf16_f32 v163, v86, v87
	ds_read_b64_tr_b16 v[84:85], v243 offset:25600
	ds_read_b64_tr_b16 v[86:87], v243 offset:26112
	v_add_f32_e32 v245, v90, v245
	v_add_f32_e32 v245, v91, v245
	v_add_f32_e32 v245, v92, v245
	v_add_f32_e32 v245, v93, v245
	v_cvt_pk_bf16_f32 v164, v88, v89
	v_cvt_pk_bf16_f32 v165, v90, v91
	ds_read_b64_tr_b16 v[88:89], v243 offset:29696
	ds_read_b64_tr_b16 v[90:91], v243 offset:30208
	v_add_f32_e32 v245, v94, v245
	v_add_f32_e32 v245, v95, v245
	v_add_f32_e32 v245, v96, v245
	v_add_f32_e32 v245, v97, v245
	v_cvt_pk_bf16_f32 v166, v92, v93
	v_cvt_pk_bf16_f32 v167, v94, v95
	ds_read_b64_tr_b16 v[92:93], v243 offset:26624
	ds_read_b64_tr_b16 v[94:95], v243 offset:27136
	v_add_f32_e32 v245, v98, v245
	v_add_f32_e32 v245, v99, v245
	v_add_f32_e32 v245, v100, v245
	v_add_f32_e32 v245, v101, v245
	v_cvt_pk_bf16_f32 v168, v96, v97
	v_cvt_pk_bf16_f32 v169, v98, v99
	ds_read_b64_tr_b16 v[96:97], v243 offset:30720
	ds_read_b64_tr_b16 v[98:99], v243 offset:31232
	v_add_f32_e32 v245, v102, v245
	v_add_f32_e32 v245, v103, v245
	v_add_f32_e32 v245, v104, v245
	v_add_f32_e32 v245, v105, v245
	v_cvt_pk_bf16_f32 v170, v100, v101
	v_cvt_pk_bf16_f32 v171, v102, v103
	ds_read_b64_tr_b16 v[100:101], v243 offset:27648
	ds_read_b64_tr_b16 v[102:103], v243 offset:28160
	v_add_f32_e32 v245, v106, v245
	v_add_f32_e32 v245, v107, v245
	v_add_f32_e32 v245, v108, v245
	v_add_f32_e32 v245, v109, v245
	v_cvt_pk_bf16_f32 v172, v104, v105
	v_cvt_pk_bf16_f32 v173, v106, v107
	ds_read_b64_tr_b16 v[104:105], v243 offset:31744
	ds_read_b64_tr_b16 v[106:107], v243 offset:32256
	v_add_f32_e32 v245, v110, v245
	v_add_f32_e32 v245, v111, v245
	v_cvt_pk_bf16_f32 v174, v108, v109
	v_cvt_pk_bf16_f32 v175, v110, v111
	v_add_f32_e32 v211, v211, v245
	s_waitcnt lgkmcnt(8)
	v_mfma_f32_32x32x16_bf16 v[0:15], v[160:163], v[214:217], v[0:15]
	ds_read_b64_tr_b16 v[214:215], v243 offset:49152
	ds_read_b64_tr_b16 v[216:217], v243 offset:49664
	v_mfma_f32_32x32x16_bf16 v[16:31], v[160:163], v[80:83], v[16:31]
	ds_read_b64_tr_b16 v[80:81], v243 offset:53248
	ds_read_b64_tr_b16 v[82:83], v243 offset:53760
	v_mfma_f32_32x32x16_bf16 v[0:15], v[164:167], v[84:87], v[0:15]
	ds_read_b64_tr_b16 v[84:85], v243 offset:50176
	ds_read_b64_tr_b16 v[86:87], v243 offset:50688
	v_mfma_f32_32x32x16_bf16 v[16:31], v[164:167], v[88:91], v[16:31]
	ds_read_b64_tr_b16 v[88:89], v243 offset:54272
	ds_read_b64_tr_b16 v[90:91], v243 offset:54784
	s_waitcnt lgkmcnt(8)
	v_mfma_f32_32x32x16_bf16 v[0:15], v[168:171], v[92:95], v[0:15]
	ds_read_b64_tr_b16 v[92:93], v243 offset:51200
	ds_read_b64_tr_b16 v[94:95], v243 offset:51712
	v_mfma_f32_32x32x16_bf16 v[16:31], v[168:171], v[96:99], v[16:31]
	ds_read_b64_tr_b16 v[96:97], v243 offset:55296
	ds_read_b64_tr_b16 v[98:99], v243 offset:55808
	v_mfma_f32_32x32x16_bf16 v[0:15], v[172:175], v[100:103], v[0:15]
	ds_read_b64_tr_b16 v[100:101], v243 offset:52224
	ds_read_b64_tr_b16 v[102:103], v243 offset:52736
	v_mfma_f32_32x32x16_bf16 v[16:31], v[172:175], v[104:107], v[16:31]
	ds_read_b64_tr_b16 v[104:105], v243 offset:56320
	ds_read_b64_tr_b16 v[106:107], v243 offset:56832
	s_waitcnt lgkmcnt(8)
	v_mfma_f32_32x32x16_bf16 v[32:47], v[160:163], v[214:217], v[32:47]
	v_mfma_f32_32x32x16_bf16 v[48:63], v[160:163], v[80:83], v[48:63]
	v_mfma_f32_32x32x16_bf16 v[32:47], v[164:167], v[84:87], v[32:47]
	v_mfma_f32_32x32x16_bf16 v[48:63], v[164:167], v[88:91], v[48:63]
	s_waitcnt lgkmcnt(0)
	v_mfma_f32_32x32x16_bf16 v[32:47], v[168:171], v[92:95], v[32:47]
	v_mfma_f32_32x32x16_bf16 v[48:63], v[168:171], v[96:99], v[48:63]
	v_mfma_f32_32x32x16_bf16 v[32:47], v[172:175], v[100:103], v[32:47]
	v_mfma_f32_32x32x16_bf16 v[48:63], v[172:175], v[104:107], v[48:63]
	s_branch .Lat_T1_end
.Lat_T1_empty:
.Lat_T1_end:
	s_cmp_lg_u32 s55, 3
	s_cbranch_scc1 .Lat_epilogue

; __device__ __forceinline__ int crow(int r,int hi){return (r&3)+8*(r>>2)+4*hi;}
; template<int THRL> __device__ __forceinline__ void attn_unit(int b,int qc,int vc,int qb,const bf16*Q,const bf16*__restrict__ K,const bf16*__restrict__ V,bf16*O,char*shm,const int tid){
;     ...
;   {auto rr=__builtin_amdgcn_permlane32_swap(__float_as_uint(l_reg),__float_as_uint(l_reg),false,false);l_reg=__uint_as_float(rr[0])+__uint_as_float(rr[1]);}
;   if(hi==0)wsf[32+r32]=l_reg;asm volatile("s_waitcnt lgkmcnt(0)":::"memory");
;   float rli[16];
;   #pragma unroll
;   for(int r=0;r<16;++r)rli[r]=__builtin_amdgcn_rcpf(wsf[32+crow(r,hi)]);
;   bf16*Ow=O+(rowbase+q0+wid*QBLK)*DM+vc;
;   { bf16*stg=(bf16*)(shm+LDS_OST)+wid*2048;
;     #pragma unroll
;     for(int r=0;r<16;++r){const int orow=crow(r,hi);
;       #pragma unroll
;       for(int d0=0;d0<2;++d0)stg[orow*64+d0*32+r32]=__float2bfloat16(o[d0][r]*rli[r]);}
;     asm volatile("s_waitcnt lgkmcnt(0)":::"memory");
;     #pragma unroll
;     for(int i=0;i<4;++i){const int row=i*8+(lane>>3),ch=lane&7; const u32x4 v=*(const u32x4*)(stg+row*64+ch*8); ATTN_STORE16(Ow+(long)row*DM+ch*8,v);} }
.Lat_epilogue:
	v_mov_b32_e32 v243, v211
	s_nop 1
	v_permlane32_swap_b32_e32 v211, v243
	v_add_f32_e32 v211, v211, v243
	ds_write_b32 v226, v211 offset:128
	s_waitcnt lgkmcnt(0)
	ds_read_b128 v[80:83], v227 offset:128
	ds_read_b128 v[84:87], v227 offset:160
	ds_read_b128 v[88:91], v227 offset:192
	ds_read_b128 v[92:95], v227 offset:224
	s_waitcnt lgkmcnt(0)
	v_rcp_f32_e32 v80, v80
	v_rcp_f32_e32 v81, v81
	v_rcp_f32_e32 v82, v82
	v_rcp_f32_e32 v83, v83
	v_rcp_f32_e32 v84, v84
	v_rcp_f32_e32 v85, v85
	v_rcp_f32_e32 v86, v86
	v_rcp_f32_e32 v87, v87
	v_rcp_f32_e32 v88, v88
	v_rcp_f32_e32 v89, v89
	v_rcp_f32_e32 v90, v90
	v_rcp_f32_e32 v91, v91
	v_rcp_f32_e32 v92, v92
	v_rcp_f32_e32 v93, v93
	v_rcp_f32_e32 v94, v94
	v_rcp_f32_e32 v95, v95
	s_nop 0
	v_mul_f32_e32 v96, v0, v80
	v_cvt_pk_bf16_f32 v96, v96, v96
	ds_write_b16 v228, v96 offset:0
	v_mul_f32_e32 v97, v1, v81
	v_cvt_pk_bf16_f32 v97, v97, v97
	ds_write_b16 v228, v97 offset:128
	v_mul_f32_e32 v98, v2, v82
	v_cvt_pk_bf16_f32 v98, v98, v98
	ds_write_b16 v228, v98 offset:256
	v_mul_f32_e32 v99, v3, v83
	v_cvt_pk_bf16_f32 v99, v99, v99
	ds_write_b16 v228, v99 offset:384
	v_mul_f32_e32 v100, v4, v84
	v_cvt_pk_bf16_f32 v100, v100, v100
	ds_write_b16 v228, v100 offset:1024
	v_mul_f32_e32 v101, v5, v85
	v_cvt_pk_bf16_f32 v101, v101, v101
	ds_write_b16 v228, v101 offset:1152
	v_mul_f32_e32 v102, v6, v86
	v_cvt_pk_bf16_f32 v102, v102, v102
	ds_write_b16 v228, v102 offset:1280
	v_mul_f32_e32 v103, v7, v87
	v_cvt_pk_bf16_f32 v103, v103, v103
	ds_write_b16 v228, v103 offset:1408
	v_mul_f32_e32 v104, v8, v88
	v_cvt_pk_bf16_f32 v104, v104, v104
	ds_write_b16 v228, v104 offset:2048
	v_mul_f32_e32 v105, v9, v89
	v_cvt_pk_bf16_f32 v105, v105, v105
	ds_write_b16 v228, v105 offset:2176
	v_mul_f32_e32 v106, v10, v90
	v_cvt_pk_bf16_f32 v106, v106, v106
	ds_write_b16 v228, v106 offset:2304
	v_mul_f32_e32 v107, v11, v91
	v_cvt_pk_bf16_f32 v107, v107, v107
	ds_write_b16 v228, v107 offset:2432
	v_mul_f32_e32 v108, v12, v92
	v_cvt_pk_bf16_f32 v108, v108, v108
	ds_write_b16 v228, v108 offset:3072
	v_mul_f32_e32 v109, v13, v93
	v_cvt_pk_bf16_f32 v109, v109, v109
	ds_write_b16 v228, v109 offset:3200
	v_mul_f32_e32 v110, v14, v94
	v_cvt_pk_bf16_f32 v110, v110, v110
	ds_write_b16 v228, v110 offset:3328
	v_mul_f32_e32 v111, v15, v95
	v_cvt_pk_bf16_f32 v111, v111, v111
	ds_write_b16 v228, v111 offset:3456
	v_mul_f32_e32 v96, v16, v80
	v_cvt_pk_bf16_f32 v96, v96, v96
	ds_write_b16 v228, v96 offset:64
	v_mul_f32_e32 v97, v17, v81
	v_cvt_pk_bf16_f32 v97, v97, v97
	ds_write_b16 v228, v97 offset:192
	v_mul_f32_e32 v98, v18, v82
	v_cvt_pk_bf16_f32 v98, v98, v98
	ds_write_b16 v228, v98 offset:320
	v_mul_f32_e32 v99, v19, v83
	v_cvt_pk_bf16_f32 v99, v99, v99
	ds_write_b16 v228, v99 offset:448
	v_mul_f32_e32 v100, v20, v84
	v_cvt_pk_bf16_f32 v100, v100, v100
	ds_write_b16 v228, v100 offset:1088
	v_mul_f32_e32 v101, v21, v85
	v_cvt_pk_bf16_f32 v101, v101, v101
	ds_write_b16 v228, v101 offset:1216
	v_mul_f32_e32 v102, v22, v86
	v_cvt_pk_bf16_f32 v102, v102, v102
	ds_write_b16 v228, v102 offset:1344
	v_mul_f32_e32 v103, v23, v87
	v_cvt_pk_bf16_f32 v103, v103, v103
	ds_write_b16 v228, v103 offset:1472
	v_mul_f32_e32 v104, v24, v88
	v_cvt_pk_bf16_f32 v104, v104, v104
	ds_write_b16 v228, v104 offset:2112
	v_mul_f32_e32 v105, v25, v89
	v_cvt_pk_bf16_f32 v105, v105, v105
	ds_write_b16 v228, v105 offset:2240
	v_mul_f32_e32 v106, v26, v90
	v_cvt_pk_bf16_f32 v106, v106, v106
	ds_write_b16 v228, v106 offset:2368
	v_mul_f32_e32 v107, v27, v91
	v_cvt_pk_bf16_f32 v107, v107, v107
	ds_write_b16 v228, v107 offset:2496
	v_mul_f32_e32 v108, v28, v92
	v_cvt_pk_bf16_f32 v108, v108, v108
	ds_write_b16 v228, v108 offset:3136
	v_mul_f32_e32 v109, v29, v93
	v_cvt_pk_bf16_f32 v109, v109, v109
	ds_write_b16 v228, v109 offset:3264
	v_mul_f32_e32 v110, v30, v94
	v_cvt_pk_bf16_f32 v110, v110, v110
	ds_write_b16 v228, v110 offset:3392
	v_mul_f32_e32 v111, v31, v95
	v_cvt_pk_bf16_f32 v111, v111, v111
	ds_write_b16 v228, v111 offset:3520
	s_waitcnt lgkmcnt(0)
	ds_read_b128 v[112:115], v229 offset:0
	ds_read_b128 v[116:119], v229 offset:1024
	ds_read_b128 v[120:123], v229 offset:2048
	ds_read_b128 v[124:127], v229 offset:3072
	s_waitcnt lgkmcnt(3)
	v_mov_b32_e32 v243, v251
	global_store_dwordx4 v243, v[112:115], s[6:7] offset:0
	s_nop 1
	s_waitcnt lgkmcnt(2)
; __device__ __forceinline__ int crow(int r,int hi){return (r&3)+8*(r>>2)+4*hi;}
; template<int THRL> __device__ __forceinline__ void attn_unit(int b,int qc,int vc,int qb,const bf16*Q,const bf16*__restrict__ K,const bf16*__restrict__ V,bf16*O,char*shm,const int tid){
;     ...
;   { bf16*stg=(bf16*)(shm+LDS_OST)+wid*2048;
;     #pragma unroll
;     for(int r=0;r<16;++r){const int orow=crow(r,hi);
;       #pragma unroll
;       for(int d0=0;d0<2;++d0)stg[orow*64+d0*32+r32]=__float2bfloat16(o[d0][r]*rli[r]);}
;     asm volatile("s_waitcnt lgkmcnt(0)":::"memory");
;     #pragma unroll
;     for(int i=0;i<4;++i){const int row=i*8+(lane>>3),ch=lane&7; const u32x4 v=*(const u32x4*)(stg+row*64+ch*8); ATTN_STORE16(Ow+(long)row*DM+ch*8,v);} }
;   asm volatile("s_waitcnt lgkmcnt(0)\n\ts_barrier":::"memory");
	v_add_u32_e32 v243, 0x4000, v243
	global_store_dwordx4 v243, v[116:119], s[6:7] offset:0
	s_nop 1
	s_waitcnt lgkmcnt(1)
	v_add_u32_e32 v243, 0x4000, v243
	global_store_dwordx4 v243, v[120:123], s[6:7] offset:0
	s_nop 1
	s_waitcnt lgkmcnt(0)
	v_add_u32_e32 v243, 0x4000, v243
	global_store_dwordx4 v243, v[124:127], s[6:7] offset:0
	s_nop 1
	v_mul_f32_e32 v96, v32, v80
	v_cvt_pk_bf16_f32 v96, v96, v96
	ds_write_b16 v228, v96 offset:0
	v_mul_f32_e32 v97, v33, v81
	v_cvt_pk_bf16_f32 v97, v97, v97
	ds_write_b16 v228, v97 offset:128
	v_mul_f32_e32 v98, v34, v82
	v_cvt_pk_bf16_f32 v98, v98, v98
	ds_write_b16 v228, v98 offset:256
	v_mul_f32_e32 v99, v35, v83
	v_cvt_pk_bf16_f32 v99, v99, v99
	ds_write_b16 v228, v99 offset:384
	v_mul_f32_e32 v100, v36, v84
	v_cvt_pk_bf16_f32 v100, v100, v100
	ds_write_b16 v228, v100 offset:1024
	v_mul_f32_e32 v101, v37, v85
	v_cvt_pk_bf16_f32 v101, v101, v101
	ds_write_b16 v228, v101 offset:1152
	v_mul_f32_e32 v102, v38, v86
	v_cvt_pk_bf16_f32 v102, v102, v102
	ds_write_b16 v228, v102 offset:1280
	v_mul_f32_e32 v103, v39, v87
	v_cvt_pk_bf16_f32 v103, v103, v103
	ds_write_b16 v228, v103 offset:1408
	v_mul_f32_e32 v104, v40, v88
	v_cvt_pk_bf16_f32 v104, v104, v104
	ds_write_b16 v228, v104 offset:2048
	v_mul_f32_e32 v105, v41, v89
	v_cvt_pk_bf16_f32 v105, v105, v105
	ds_write_b16 v228, v105 offset:2176
	v_mul_f32_e32 v106, v42, v90
	v_cvt_pk_bf16_f32 v106, v106, v106
	ds_write_b16 v228, v106 offset:2304
	v_mul_f32_e32 v107, v43, v91
	v_cvt_pk_bf16_f32 v107, v107, v107
	ds_write_b16 v228, v107 offset:2432
	v_mul_f32_e32 v108, v44, v92
	v_cvt_pk_bf16_f32 v108, v108, v108
	ds_write_b16 v228, v108 offset:3072
	v_mul_f32_e32 v109, v45, v93
	v_cvt_pk_bf16_f32 v109, v109, v109
	ds_write_b16 v228, v109 offset:3200
	v_mul_f32_e32 v110, v46, v94
	v_cvt_pk_bf16_f32 v110, v110, v110
	ds_write_b16 v228, v110 offset:3328
	v_mul_f32_e32 v111, v47, v95
	v_cvt_pk_bf16_f32 v111, v111, v111
	ds_write_b16 v228, v111 offset:3456
	v_mul_f32_e32 v96, v48, v80
	v_cvt_pk_bf16_f32 v96, v96, v96
	ds_write_b16 v228, v96 offset:64
	v_mul_f32_e32 v97, v49, v81
	v_cvt_pk_bf16_f32 v97, v97, v97
	ds_write_b16 v228, v97 offset:192
	v_mul_f32_e32 v98, v50, v82
	v_cvt_pk_bf16_f32 v98, v98, v98
	ds_write_b16 v228, v98 offset:320
	v_mul_f32_e32 v99, v51, v83
	v_cvt_pk_bf16_f32 v99, v99, v99
	ds_write_b16 v228, v99 offset:448
	v_mul_f32_e32 v100, v52, v84
	v_cvt_pk_bf16_f32 v100, v100, v100
	ds_write_b16 v228, v100 offset:1088
	v_mul_f32_e32 v101, v53, v85
	v_cvt_pk_bf16_f32 v101, v101, v101
	ds_write_b16 v228, v101 offset:1216
	v_mul_f32_e32 v102, v54, v86
	v_cvt_pk_bf16_f32 v102, v102, v102
	ds_write_b16 v228, v102 offset:1344
	v_mul_f32_e32 v103, v55, v87
	v_cvt_pk_bf16_f32 v103, v103, v103
	ds_write_b16 v228, v103 offset:1472
	v_mul_f32_e32 v104, v56, v88
	v_cvt_pk_bf16_f32 v104, v104, v104
	ds_write_b16 v228, v104 offset:2112
	v_mul_f32_e32 v105, v57, v89
	v_cvt_pk_bf16_f32 v105, v105, v105
	ds_write_b16 v228, v105 offset:2240
	v_mul_f32_e32 v106, v58, v90
	v_cvt_pk_bf16_f32 v106, v106, v106
	ds_write_b16 v228, v106 offset:2368
	v_mul_f32_e32 v107, v59, v91
	v_cvt_pk_bf16_f32 v107, v107, v107
	ds_write_b16 v228, v107 offset:2496
	v_mul_f32_e32 v108, v60, v92
	v_cvt_pk_bf16_f32 v108, v108, v108
	ds_write_b16 v228, v108 offset:3136
	v_mul_f32_e32 v109, v61, v93
	v_cvt_pk_bf16_f32 v109, v109, v109
	ds_write_b16 v228, v109 offset:3264
	v_mul_f32_e32 v110, v62, v94
	v_cvt_pk_bf16_f32 v110, v110, v110
	ds_write_b16 v228, v110 offset:3392
	v_mul_f32_e32 v111, v63, v95
	v_cvt_pk_bf16_f32 v111, v111, v111
	ds_write_b16 v228, v111 offset:3520
	s_waitcnt lgkmcnt(0)
	ds_read_b128 v[112:115], v229 offset:0
	ds_read_b128 v[116:119], v229 offset:1024
	ds_read_b128 v[120:123], v229 offset:2048
	ds_read_b128 v[124:127], v229 offset:3072
	s_waitcnt lgkmcnt(3)
	v_mov_b32_e32 v243, v251
	global_store_dwordx4 v243, v[112:115], s[6:7] offset:128
	s_nop 1
	s_waitcnt lgkmcnt(2)
	v_add_u32_e32 v243, 0x4000, v243
	global_store_dwordx4 v243, v[116:119], s[6:7] offset:128
	s_nop 1
	s_waitcnt lgkmcnt(1)
	v_add_u32_e32 v243, 0x4000, v243
	global_store_dwordx4 v243, v[120:123], s[6:7] offset:128
	s_nop 1
	s_waitcnt lgkmcnt(0)
	v_add_u32_e32 v243, 0x4000, v243
	global_store_dwordx4 v243, v[124:127], s[6:7] offset:128
	s_nop 1
	s_waitcnt lgkmcnt(0)
	s_barrier
	s_branch .Lat_unit_done
